# scan redesigned: waves 0-3 compute with 2 rows x 4 k per lane (half the LDS bytes per state element), waves 4-7 stage inputs
# speedup vs baseline: 1.0228x; 1.0143x over previous
; __device__ __forceinline__ void phase_scan(CParams& P, LAS unsigned char* lds) {
;     ...
;     for (int task = vcu_; task < GSEQ * 8 * 2 * 2; task += nb_) {
;         const int rowhalf = task & 1, dir = (task >> 1) & 1, h = (task >> 2) & 7, s = task >> 5;
;         float* OUT = (float*)(P.ws + WS_P2) + (size_t)dir * TG * 512;
;         __syncthreads();
;         if (wid >= 4) {
;             const int ltid = tid - 256; f16x8 v[6];
;     ...
;             SC_GLOAD(0); SC_WRITE(0); SC_GLOAD(1);
.LBB0_235:
	s_andn2_b64 vcc, exec, s[4:5]
	s_cbranch_vccnz .LBB0_627
	s_cmp_gt_i32 s14, 8
	s_mov_b64 s[4:5], -1
	s_cbranch_scc0 .LBB0_606
	s_waitcnt vmcnt(0)
	s_and_b32 s4, s2, 7
	s_lshl_b32 s4, s4, 5
	s_lshr_b32 s5, s2, 3
	s_add_i32 s4, s4, s5
	s_and_b32 s8, s4, 1
	s_bfe_u32 s5, s4, 0x10001
	s_bfe_u32 s6, s4, 0x30002
	s_lshr_b32 s7, s4, 5
	s_mul_i32 s9, s7, 0xc00000
	s_mul_i32 s12, s6, 0x180
	s_add_i32 s9, s9, s12
	s_add_i32 s12, s9, 0x1a000000
	s_add_u32 s40, s22, s12
	s_addc_u32 s41, s23, 0
	s_mul_i32 s12, s5, 0x6000000
	s_add_i32 s12, s12, s9
	s_add_i32 s12, s12, 0x20000000
	s_add_u32 s42, s22, s12
	s_addc_u32 s43, s23, 0
	s_lshl_b32 s12, s7, 22
	s_lshl_b32 s15, s6, 7
	s_add_i32 s12, s12, s15
	s_lshl_b32 s15, s8, 6
	s_add_i32 s12, s12, s15
	s_add_i32 s12, s12, 0x2e000000
	s_add_u32 s44, s22, s12
	s_addc_u32 s45, s23, 0
	s_lshl_b32 s12, s7, 23
	s_lshl_b32 s15, s6, 8
	s_add_i32 s12, s12, s15
	s_lshl_b32 s15, s8, 7
	s_add_i32 s12, s12, s15
	s_lshl_b32 s15, s5, 26
	s_add_i32 s12, s12, s15
	s_add_i32 s12, s12, 0x8000000
	s_add_u32 s10, s22, s12
	s_addc_u32 s11, s23, 0
	s_cmp_eq_u32 s5, 0
	s_cselect_b32 s46, 0, 0xfff
	s_mov_b32 s47, 0xfffe8000
	s_cselect_b32 s48, 0x18000, s47
	s_cselect_b32 s49, 0, -1
	s_mov_b32 s47, 0xffff8000
	s_cselect_b32 s36, 0x8000, s47
	s_cselect_b32 s37, 0, -1
	s_mov_b32 s47, 0xffff4000
	s_cselect_b32 s54, 0xc000, s47
	s_cselect_b32 s55, 0, -1
	s_mov_b32 s47, 0xffffe000
	s_cselect_b32 s13, 0x2000, s47
	s_mov_b32 s50, 0xaaaaaaaa
	s_mov_b32 s51, 0xaaaaaaaa
	s_mov_b32 s52, 0xcccccccc
	s_mov_b32 s53, 0xcccccccc
	v_lshrrev_b32_e32 v0, 6, v222
	v_and_b32_e32 v6, 15, v222
	v_readfirstlane_b32 s28, v0
	v_lshrrev_b32_e32 v7, 4, v222
	s_mov_b32 s12, 0
	s_mov_b32 s14, 0
	s_cmp_lt_u32 s28, 4
	s_cbranch_scc1 .Lr2_compute
	v_and_b32_e32 v0, 0xff, v222
	v_lshrrev_b32_e32 v7, 4, v0
	v_xor_b32_e32 v1, s46, v7
	v_mul_u32_u24_e32 v1, 0xc00, v1
	v_lshlrev_b32_e32 v64, 4, v6
	v_add_u32_e32 v130, v1, v64
	v_mov_b32_e32 v131, 0
	v_and_b32_e32 v1, 8, v6
	v_lshlrev_b32_e32 v1, 4, v1
	v_add_u32_e32 v128, v130, v1
	v_mov_b32_e32 v129, 0
	v_lshl_add_u64 v[74:75], s[40:41], 0, v[128:129]
	v_lshl_add_u64 v[78:79], s[42:43], 0, v[130:131]
	v_lshl_add_u64 v[76:77], v[74:75], 0, s[54:55]
	v_lshl_add_u64 v[80:81], v[78:79], 0, s[54:55]
	v_mul_u32_u24_e32 v2, 0x500, v7
	v_and_b32_e32 v1, 7, v6
	v_lshlrev_b32_e32 v1, 5, v1
	v_add_u32_e32 v2, v2, v1
	v_and_b32_e32 v1, 8, v6
	v_lshlrev_b32_e32 v127, 7, v1
	v_sub_u32_e32 v127, 0x400, v127
	v_add_u32_e32 v118, v2, v127
	v_lshlrev_b32_e32 v127, 5, v1
	v_add_u32_e32 v127, 0x100, v127
	v_add_u32_e32 v119, v2, v127
	v_lshrrev_b32_e32 v2, 3, v0
	v_and_b32_e32 v1, 7, v0
	v_xor_b32_e32 v127, s46, v2
	v_mul_u32_u24_e32 v127, 0xc00, v127
	v_lshlrev_b32_e32 v128, 4, v1
	v_add_u32_e32 v128, v127, v128
	v_add_u32_e32 v128, 0x100, v128
	v_mov_b32_e32 v129, 0
	v_lshl_add_u64 v[82:83], s[42:43], 0, v[128:129]
	v_mul_u32_u24_e32 v2, 0x500, v2
	v_lshlrev_b32_e32 v1, 5, v1
	v_add_u32_e32 v2, v2, v1
	v_add_u32_e32 v120, 0x300, v2
	v_lshrrev_b32_e32 v2, 2, v0
	v_and_b32_e32 v2, 31, v2
	v_and_b32_e32 v1, 3, v0
	v_xor_b32_e32 v127, s46, v2
	v_lshlrev_b32_e32 v127, 10, v127
	v_lshlrev_b32_e32 v128, 4, v1
	v_add_u32_e32 v128, v127, v128
	v_mov_b32_e32 v129, 0
	v_lshl_add_u64 v[84:85], s[44:45], 0, v[128:129]
	v_lshlrev_b32_e32 v2, 3, v2
	v_lshlrev_b32_e32 v1, 10, v1
	v_add_u32_e32 v2, v2, v1
	v_add_u32_e32 v121, 0xa000, v2
	global_load_dwordx4 v[86:89], v[74:75], off
	global_load_dwordx4 v[90:93], v[76:77], off
	global_load_dwordx4 v[94:97], v[78:79], off
	global_load_dwordx4 v[98:101], v[80:81], off
	global_load_dwordx4 v[102:105], v[82:83], off
	v_lshl_add_u64 v[74:75], v[74:75], 0, s[48:49]
	v_lshl_add_u64 v[76:77], v[76:77], 0, s[48:49]
	v_lshl_add_u64 v[78:79], v[78:79], 0, s[48:49]
	v_lshl_add_u64 v[80:81], v[80:81], 0, s[48:49]
	v_lshl_add_u64 v[82:83], v[82:83], 0, s[48:49]
	s_cmp_lt_u32 s28, 6
	s_cbranch_scc0 .Lr2_noV1
	global_load_dwordx4 v[106:109], v[84:85], off
	v_lshl_add_u64 v[84:85], v[84:85], 0, s[36:37]
.Lr2_noV1:
	s_waitcnt vmcnt(0)
	v_add_u32_e32 v122, s14, v118
	v_cvt_f32_f16_e32 v110, v86
	v_cvt_f32_f16_sdwa v111, v86 dst_sel:DWORD dst_unused:UNUSED_PAD src0_sel:WORD_1
	v_cvt_f32_f16_e32 v112, v87
	v_cvt_f32_f16_sdwa v113, v87 dst_sel:DWORD dst_unused:UNUSED_PAD src0_sel:WORD_1
	v_cvt_f32_f16_e32 v114, v88
	v_cvt_f32_f16_sdwa v115, v88 dst_sel:DWORD dst_unused:UNUSED_PAD src0_sel:WORD_1
	v_cvt_f32_f16_e32 v116, v89
	v_cvt_f32_f16_sdwa v117, v89 dst_sel:DWORD dst_unused:UNUSED_PAD src0_sel:WORD_1
	ds_write_b128 v122, v[110:113] offset:0
	ds_write_b128 v122, v[114:117] offset:16
	v_add_u32_e32 v122, s14, v118
	v_cvt_f32_f16_e32 v110, v90
	v_cvt_f32_f16_sdwa v111, v90 dst_sel:DWORD dst_unused:UNUSED_PAD src0_sel:WORD_1
	v_cvt_f32_f16_e32 v112, v91
	v_cvt_f32_f16_sdwa v113, v91 dst_sel:DWORD dst_unused:UNUSED_PAD src0_sel:WORD_1
	v_cvt_f32_f16_e32 v114, v92
	v_cvt_f32_f16_sdwa v115, v92 dst_sel:DWORD dst_unused:UNUSED_PAD src0_sel:WORD_1
	v_cvt_f32_f16_e32 v116, v93
	v_cvt_f32_f16_sdwa v117, v93 dst_sel:DWORD dst_unused:UNUSED_PAD src0_sel:WORD_1
	ds_write_b128 v122, v[110:113] offset:20480
	ds_write_b128 v122, v[114:117] offset:20496
	v_add_u32_e32 v122, s14, v119
	v_cvt_f32_f16_e32 v110, v94
	v_cvt_f32_f16_sdwa v111, v94 dst_sel:DWORD dst_unused:UNUSED_PAD src0_sel:WORD_1
	v_cvt_f32_f16_e32 v112, v95
	v_cvt_f32_f16_sdwa v113, v95 dst_sel:DWORD dst_unused:UNUSED_PAD src0_sel:WORD_1
	v_cvt_f32_f16_e32 v114, v96
	v_cvt_f32_f16_sdwa v115, v96 dst_sel:DWORD dst_unused:UNUSED_PAD src0_sel:WORD_1
	v_cvt_f32_f16_e32 v116, v97
	v_cvt_f32_f16_sdwa v117, v97 dst_sel:DWORD dst_unused:UNUSED_PAD src0_sel:WORD_1
	ds_write_b128 v122, v[110:113] offset:0
	ds_write_b128 v122, v[114:117] offset:16
	v_add_u32_e32 v122, s14, v119
	v_cvt_f32_f16_e32 v110, v98
	v_cvt_f32_f16_sdwa v111, v98 dst_sel:DWORD dst_unused:UNUSED_PAD src0_sel:WORD_1
	v_cvt_f32_f16_e32 v112, v99
	v_cvt_f32_f16_sdwa v113, v99 dst_sel:DWORD dst_unused:UNUSED_PAD src0_sel:WORD_1
	v_cvt_f32_f16_e32 v114, v100
	v_cvt_f32_f16_sdwa v115, v100 dst_sel:DWORD dst_unused:UNUSED_PAD src0_sel:WORD_1
	v_cvt_f32_f16_e32 v116, v101
	v_cvt_f32_f16_sdwa v117, v101 dst_sel:DWORD dst_unused:UNUSED_PAD src0_sel:WORD_1
	ds_write_b128 v122, v[110:113] offset:20480
	ds_write_b128 v122, v[114:117] offset:20496
	v_add_u32_e32 v122, s14, v120
	v_cvt_f32_f16_e32 v110, v102
	v_cvt_f32_f16_sdwa v111, v102 dst_sel:DWORD dst_unused:UNUSED_PAD src0_sel:WORD_1
	v_cvt_f32_f16_e32 v112, v103
	v_cvt_f32_f16_sdwa v113, v103 dst_sel:DWORD dst_unused:UNUSED_PAD src0_sel:WORD_1
	v_cvt_f32_f16_e32 v114, v104
	v_cvt_f32_f16_sdwa v115, v104 dst_sel:DWORD dst_unused:UNUSED_PAD src0_sel:WORD_1
	v_cvt_f32_f16_e32 v116, v105
	v_cvt_f32_f16_sdwa v117, v105 dst_sel:DWORD dst_unused:UNUSED_PAD src0_sel:WORD_1
	ds_write_b128 v122, v[110:113] offset:0
	ds_write_b128 v122, v[114:117] offset:16
	s_cmp_lt_u32 s28, 6
	s_cbranch_scc0 .Lr2_nowV2
; __device__ __forceinline__ void phase_scan(CParams& P, LAS unsigned char* lds) {
;     ...
;         if (wid >= 4) {
;             const int ltid = tid - 256; f16x8 v[6];
;     ...
;             SC_GLOAD(0); SC_WRITE(0); SC_GLOAD(1);
; #pragma unroll 1
;             for (int c = 0; c < NCH; ++c) {
;                 __syncthreads();
;                 if (c + 1 < NCH) { SC_WRITE(c + 1); if (c + 2 < NCH) SC_GLOAD(c + 2); }
;             }
;             __syncthreads();
	v_add_u32_e32 v122, s14, v121
	v_cvt_f32_f16_e32 v110, v106
	v_cvt_f32_f16_sdwa v111, v106 dst_sel:DWORD dst_unused:UNUSED_PAD src0_sel:WORD_1
	v_cvt_f32_f16_e32 v112, v107
	v_cvt_f32_f16_sdwa v113, v107 dst_sel:DWORD dst_unused:UNUSED_PAD src0_sel:WORD_1
	v_cvt_f32_f16_e32 v114, v108
	v_cvt_f32_f16_sdwa v115, v108 dst_sel:DWORD dst_unused:UNUSED_PAD src0_sel:WORD_1
	v_cvt_f32_f16_e32 v116, v109
	v_cvt_f32_f16_sdwa v117, v109 dst_sel:DWORD dst_unused:UNUSED_PAD src0_sel:WORD_1
	ds_write_b64 v122, v[110:111] offset:0
	ds_write_b64 v122, v[112:113] offset:256
	ds_write_b64 v122, v[114:115] offset:512
	ds_write_b64 v122, v[116:117] offset:768
.Lr2_nowV2:
	global_load_dwordx4 v[86:89], v[74:75], off
	global_load_dwordx4 v[90:93], v[76:77], off
	global_load_dwordx4 v[94:97], v[78:79], off
	global_load_dwordx4 v[98:101], v[80:81], off
	global_load_dwordx4 v[102:105], v[82:83], off
	v_lshl_add_u64 v[74:75], v[74:75], 0, s[48:49]
	v_lshl_add_u64 v[76:77], v[76:77], 0, s[48:49]
	v_lshl_add_u64 v[78:79], v[78:79], 0, s[48:49]
	v_lshl_add_u64 v[80:81], v[80:81], 0, s[48:49]
	v_lshl_add_u64 v[82:83], v[82:83], 0, s[48:49]
	s_cmp_lt_u32 s28, 6
	s_cbranch_scc0 .Lr2_noV3
	global_load_dwordx4 v[106:109], v[84:85], off
	v_lshl_add_u64 v[84:85], v[84:85], 0, s[36:37]
.Lr2_noV3:
.Lr2_lchunk:
	s_waitcnt lgkmcnt(0)
	s_barrier
	s_cmp_ge_u32 s12, 0x7f
	s_cbranch_scc1 .Lr2_lskip
	s_waitcnt vmcnt(0)
	s_sub_i32 s15, 0xb000, s14
	v_add_u32_e32 v122, s15, v118
	v_cvt_f32_f16_e32 v110, v86
	v_cvt_f32_f16_sdwa v111, v86 dst_sel:DWORD dst_unused:UNUSED_PAD src0_sel:WORD_1
	v_cvt_f32_f16_e32 v112, v87
	v_cvt_f32_f16_sdwa v113, v87 dst_sel:DWORD dst_unused:UNUSED_PAD src0_sel:WORD_1
	v_cvt_f32_f16_e32 v114, v88
	v_cvt_f32_f16_sdwa v115, v88 dst_sel:DWORD dst_unused:UNUSED_PAD src0_sel:WORD_1
	v_cvt_f32_f16_e32 v116, v89
	v_cvt_f32_f16_sdwa v117, v89 dst_sel:DWORD dst_unused:UNUSED_PAD src0_sel:WORD_1
	ds_write_b128 v122, v[110:113] offset:0
	ds_write_b128 v122, v[114:117] offset:16
	v_add_u32_e32 v122, s15, v118
	v_cvt_f32_f16_e32 v110, v90
	v_cvt_f32_f16_sdwa v111, v90 dst_sel:DWORD dst_unused:UNUSED_PAD src0_sel:WORD_1
	v_cvt_f32_f16_e32 v112, v91
	v_cvt_f32_f16_sdwa v113, v91 dst_sel:DWORD dst_unused:UNUSED_PAD src0_sel:WORD_1
	v_cvt_f32_f16_e32 v114, v92
	v_cvt_f32_f16_sdwa v115, v92 dst_sel:DWORD dst_unused:UNUSED_PAD src0_sel:WORD_1
	v_cvt_f32_f16_e32 v116, v93
	v_cvt_f32_f16_sdwa v117, v93 dst_sel:DWORD dst_unused:UNUSED_PAD src0_sel:WORD_1
	ds_write_b128 v122, v[110:113] offset:20480
	ds_write_b128 v122, v[114:117] offset:20496
	v_add_u32_e32 v122, s15, v119
	v_cvt_f32_f16_e32 v110, v94
	v_cvt_f32_f16_sdwa v111, v94 dst_sel:DWORD dst_unused:UNUSED_PAD src0_sel:WORD_1
	v_cvt_f32_f16_e32 v112, v95
	v_cvt_f32_f16_sdwa v113, v95 dst_sel:DWORD dst_unused:UNUSED_PAD src0_sel:WORD_1
	v_cvt_f32_f16_e32 v114, v96
	v_cvt_f32_f16_sdwa v115, v96 dst_sel:DWORD dst_unused:UNUSED_PAD src0_sel:WORD_1
	v_cvt_f32_f16_e32 v116, v97
	v_cvt_f32_f16_sdwa v117, v97 dst_sel:DWORD dst_unused:UNUSED_PAD src0_sel:WORD_1
	ds_write_b128 v122, v[110:113] offset:0
	ds_write_b128 v122, v[114:117] offset:16
	v_add_u32_e32 v122, s15, v119
	v_cvt_f32_f16_e32 v110, v98
	v_cvt_f32_f16_sdwa v111, v98 dst_sel:DWORD dst_unused:UNUSED_PAD src0_sel:WORD_1
	v_cvt_f32_f16_e32 v112, v99
	v_cvt_f32_f16_sdwa v113, v99 dst_sel:DWORD dst_unused:UNUSED_PAD src0_sel:WORD_1
	v_cvt_f32_f16_e32 v114, v100
	v_cvt_f32_f16_sdwa v115, v100 dst_sel:DWORD dst_unused:UNUSED_PAD src0_sel:WORD_1
	v_cvt_f32_f16_e32 v116, v101
	v_cvt_f32_f16_sdwa v117, v101 dst_sel:DWORD dst_unused:UNUSED_PAD src0_sel:WORD_1
	ds_write_b128 v122, v[110:113] offset:20480
	ds_write_b128 v122, v[114:117] offset:20496
	v_add_u32_e32 v122, s15, v120
	v_cvt_f32_f16_e32 v110, v102
	v_cvt_f32_f16_sdwa v111, v102 dst_sel:DWORD dst_unused:UNUSED_PAD src0_sel:WORD_1
	v_cvt_f32_f16_e32 v112, v103
	v_cvt_f32_f16_sdwa v113, v103 dst_sel:DWORD dst_unused:UNUSED_PAD src0_sel:WORD_1
	v_cvt_f32_f16_e32 v114, v104
	v_cvt_f32_f16_sdwa v115, v104 dst_sel:DWORD dst_unused:UNUSED_PAD src0_sel:WORD_1
	v_cvt_f32_f16_e32 v116, v105
	v_cvt_f32_f16_sdwa v117, v105 dst_sel:DWORD dst_unused:UNUSED_PAD src0_sel:WORD_1
	ds_write_b128 v122, v[110:113] offset:0
	ds_write_b128 v122, v[114:117] offset:16
	s_cmp_lt_u32 s28, 6
	s_cbranch_scc0 .Lr2_nowV4
	v_add_u32_e32 v122, s15, v121
	v_cvt_f32_f16_e32 v110, v106
	v_cvt_f32_f16_sdwa v111, v106 dst_sel:DWORD dst_unused:UNUSED_PAD src0_sel:WORD_1
	v_cvt_f32_f16_e32 v112, v107
	v_cvt_f32_f16_sdwa v113, v107 dst_sel:DWORD dst_unused:UNUSED_PAD src0_sel:WORD_1
	v_cvt_f32_f16_e32 v114, v108
	v_cvt_f32_f16_sdwa v115, v108 dst_sel:DWORD dst_unused:UNUSED_PAD src0_sel:WORD_1
	v_cvt_f32_f16_e32 v116, v109
	v_cvt_f32_f16_sdwa v117, v109 dst_sel:DWORD dst_unused:UNUSED_PAD src0_sel:WORD_1
	ds_write_b64 v122, v[110:111] offset:0
	ds_write_b64 v122, v[112:113] offset:256
	ds_write_b64 v122, v[114:115] offset:512
	ds_write_b64 v122, v[116:117] offset:768
.Lr2_nowV4:
	s_cmp_ge_u32 s12, 0x7e
	s_cbranch_scc1 .Lr2_lskip
	global_load_dwordx4 v[86:89], v[74:75], off
	global_load_dwordx4 v[90:93], v[76:77], off
	global_load_dwordx4 v[94:97], v[78:79], off
	global_load_dwordx4 v[98:101], v[80:81], off
	global_load_dwordx4 v[102:105], v[82:83], off
	v_lshl_add_u64 v[74:75], v[74:75], 0, s[48:49]
	v_lshl_add_u64 v[76:77], v[76:77], 0, s[48:49]
	v_lshl_add_u64 v[78:79], v[78:79], 0, s[48:49]
	v_lshl_add_u64 v[80:81], v[80:81], 0, s[48:49]
	v_lshl_add_u64 v[82:83], v[82:83], 0, s[48:49]
	s_cmp_lt_u32 s28, 6
	s_cbranch_scc0 .Lr2_noV5
	global_load_dwordx4 v[106:109], v[84:85], off
	v_lshl_add_u64 v[84:85], v[84:85], 0, s[36:37]
; #define LAS __attribute__((address_space(3)))
; __device__ __forceinline__ void phase_scan(CParams& P, LAS unsigned char* lds) {
;     ...
;                 if (c + 1 < NCH) { SC_WRITE(c + 1); if (c + 2 < NCH) SC_GLOAD(c + 2); }
;             }
;             __syncthreads();
;     ...
;         } else {
;             const int rl = lane >> 3, oct = lane & 7, rloc = wid * 8 + rl;
;             __builtin_amdgcn_s_setprio(3);
;             f32x4 s0 = {0.f, 0.f, 0.f, 0.f}, s1 = {0.f, 0.f, 0.f, 0.f};
;             float* op = OUT + ((size_t)s * SEQ + (dir ? SEQ - 1 : 0)) * 512 + h * 64 + rowhalf * 32 + rloc; const long ostep = dir ? -512 : 512;
;     ...
;             f32x4 Ar0, Ar1, Aw0, Aw1, Ak0, Ak1, Aq0, Aq1, Ab0, Ab1, Br0, Br1, Bw0, Bw1, Bk0, Bk1, Bq0, Bq1, Bb0, Bb1; float Avv, Bvv;
; #pragma unroll 1
;             for (int c = 0; c < NCH; ++c) {
;                 __syncthreads();
;                 const LAS float* base = lf + (c & 1) * BUFF + 8 * oct;
;                 SC_LOAD(A, base);
.Lr2_noV5:
.Lr2_lskip:
	s_xor_b32 s14, s14, 0xb000
	s_add_i32 s12, s12, 1
	s_cmp_lt_u32 s12, 0x80
	s_cbranch_scc1 .Lr2_lchunk
	s_branch .Lr2_done
.Lr2_compute:
	v_lshlrev_b32_e32 v98, 4, v6
	v_lshlrev_b32_e32 v0, 8, v7
	v_add_u32_e32 v99, 0xa000, v0
	v_and_b32_e32 v0, 3, v6
	v_xor_b32_e32 v0, s46, v0
	v_lshlrev_b32_e32 v0, 11, v0
	v_lshl_add_u32 v102, v7, 3, v0
	v_mov_b32_e32 v2, 0
	v_mov_b32_e32 v3, 0
	v_mov_b32_e32 v4, 0
	v_mov_b32_e32 v5, 0
	v_mov_b32_e32 v6, 0
	v_mov_b32_e32 v7, 0
	v_mov_b32_e32 v8, 0
	v_mov_b32_e32 v9, 0
.Lr2_chunk:
	s_waitcnt lgkmcnt(0)
	s_barrier
	v_add_u32_e32 v100, s14, v98
	v_add_u32_e32 v101, s14, v99
	ds_read_b128 v[70:73], v101 offset:0
	ds_read_b128 v[10:13], v100 offset:0
	ds_read_b128 v[18:21], v100 offset:512
	ds_read_b128 v[14:17], v100 offset:256
	ds_read_b128 v[22:25], v100 offset:768
	ds_read_b128 v[26:29], v100 offset:1024
	ds_read_b128 v[30:33], v100 offset:1280
	ds_read_b128 v[38:41], v100 offset:1792
	ds_read_b128 v[34:37], v100 offset:1536
	ds_read_b128 v[42:45], v100 offset:2048
	ds_read_b128 v[46:49], v100 offset:2304
	s_waitcnt lgkmcnt(5)
	v_pk_mul_f32 v[78:79], v[2:3], v[10:11] op_sel_hi:[1,0]
	v_pk_fma_f32 v[78:79], v[4:5], v[10:11], v[78:79] op_sel:[0,1,0] op_sel_hi:[1,1,1]
	v_pk_fma_f32 v[78:79], v[6:7], v[12:13], v[78:79] op_sel_hi:[1,0,1]
	v_pk_fma_f32 v[78:79], v[8:9], v[12:13], v[78:79] op_sel:[0,1,0] op_sel_hi:[1,1,1]
	v_pk_mul_f32 v[82:83], v[70:71], v[18:19] op_sel_hi:[1,0]
	v_pk_mul_f32 v[84:85], v[70:71], v[18:19] op_sel:[0,1] op_sel_hi:[1,1]
	v_add_f32_dpp v78, v78, v78 quad_perm:[1,0,3,2] row_mask:0xf bank_mask:0xf bound_ctrl:1
	v_add_f32_dpp v79, v79, v79 quad_perm:[1,0,3,2] row_mask:0xf bank_mask:0xf bound_ctrl:1
	v_pk_mul_f32 v[86:87], v[70:71], v[20:21] op_sel_hi:[1,0]
	ds_read_b128 v[132:135], v100 offset:2560
	v_add_f32_dpp v78, v78, v78 quad_perm:[2,3,0,1] row_mask:0xf bank_mask:0xf bound_ctrl:1
	v_add_f32_dpp v79, v79, v79 quad_perm:[2,3,0,1] row_mask:0xf bank_mask:0xf bound_ctrl:1
	v_pk_mul_f32 v[88:89], v[70:71], v[20:21] op_sel:[0,1] op_sel_hi:[1,1]
	ds_read_b128 v[140:143], v100 offset:3072
	v_add_f32_dpp v78, v78, v78 row_half_mirror row_mask:0xf bank_mask:0xf bound_ctrl:1
	v_add_f32_dpp v79, v79, v79 row_half_mirror row_mask:0xf bank_mask:0xf bound_ctrl:1
	v_pk_fma_f32 v[82:83], v[2:3], v[14:15], v[82:83] op_sel_hi:[1,0,1]
	ds_read_b128 v[136:139], v100 offset:2816
	v_add_f32_dpp v78, v78, v78 row_mirror row_mask:0xf bank_mask:0xf bound_ctrl:1
	v_add_f32_dpp v79, v79, v79 row_mirror row_mask:0xf bank_mask:0xf bound_ctrl:1
	v_pk_fma_f32 v[84:85], v[4:5], v[14:15], v[84:85] op_sel:[0,1,0] op_sel_hi:[1,1,1]
	ds_read_b128 v[144:147], v100 offset:3328
	v_pk_fma_f32 v[86:87], v[6:7], v[16:17], v[86:87] op_sel_hi:[1,0,1]
	ds_read_b128 v[148:151], v100 offset:3584
	v_pk_fma_f32 v[88:89], v[8:9], v[16:17], v[88:89] op_sel:[0,1,0] op_sel_hi:[1,1,1]
	ds_read_b128 v[74:77], v101 offset:16
	v_pk_fma_f32 v[2:3], v[78:79], v[22:23], v[82:83] op_sel_hi:[1,0,1]
	v_pk_fma_f32 v[4:5], v[78:79], v[22:23], v[84:85] op_sel:[0,1,0] op_sel_hi:[1,1,1]
	v_pk_fma_f32 v[6:7], v[78:79], v[24:25], v[86:87] op_sel_hi:[1,0,1]
	v_pk_fma_f32 v[8:9], v[78:79], v[24:25], v[88:89] op_sel:[0,1,0] op_sel_hi:[1,1,1]
	s_waitcnt lgkmcnt(6)
	v_pk_mul_f32 v[78:79], v[2:3], v[30:31] op_sel_hi:[1,0]
	v_pk_mul_f32 v[90:91], v[2:3], v[26:27] op_sel_hi:[1,0]
	v_pk_fma_f32 v[78:79], v[4:5], v[30:31], v[78:79] op_sel:[0,1,0] op_sel_hi:[1,1,1]
	v_pk_fma_f32 v[90:91], v[4:5], v[26:27], v[90:91] op_sel:[0,1,0] op_sel_hi:[1,1,1]
	v_pk_fma_f32 v[78:79], v[6:7], v[32:33], v[78:79] op_sel_hi:[1,0,1]
	v_pk_fma_f32 v[90:91], v[6:7], v[28:29], v[90:91] op_sel_hi:[1,0,1]
	v_pk_fma_f32 v[78:79], v[8:9], v[32:33], v[78:79] op_sel:[0,1,0] op_sel_hi:[1,1,1]
	v_pk_mul_f32 v[82:83], v[72:73], v[38:39] op_sel_hi:[1,0]
	v_pk_fma_f32 v[90:91], v[8:9], v[28:29], v[90:91] op_sel:[0,1,0] op_sel_hi:[1,1,1]
	v_pk_mul_f32 v[84:85], v[72:73], v[38:39] op_sel:[0,1] op_sel_hi:[1,1]
	v_add_f32_dpp v78, v78, v78 quad_perm:[1,0,3,2] row_mask:0xf bank_mask:0xf bound_ctrl:1
	v_add_f32_dpp v79, v79, v79 quad_perm:[1,0,3,2] row_mask:0xf bank_mask:0xf bound_ctrl:1
	v_pk_mul_f32 v[86:87], v[72:73], v[40:41] op_sel_hi:[1,0]
	ds_read_b128 v[10:13], v100 offset:3840
	v_add_f32_dpp v78, v78, v78 quad_perm:[2,3,0,1] row_mask:0xf bank_mask:0xf bound_ctrl:1
	v_add_f32_dpp v79, v79, v79 quad_perm:[2,3,0,1] row_mask:0xf bank_mask:0xf bound_ctrl:1
	v_pk_mul_f32 v[88:89], v[72:73], v[40:41] op_sel:[0,1] op_sel_hi:[1,1]
	ds_read_b128 v[18:21], v100 offset:4352
	v_add_f32_dpp v78, v78, v78 row_half_mirror row_mask:0xf bank_mask:0xf bound_ctrl:1
	v_add_f32_dpp v79, v79, v79 row_half_mirror row_mask:0xf bank_mask:0xf bound_ctrl:1
	v_pk_fma_f32 v[82:83], v[2:3], v[34:35], v[82:83] op_sel_hi:[1,0,1]
	ds_read_b128 v[14:17], v100 offset:4096
	v_add_f32_dpp v78, v78, v78 row_mirror row_mask:0xf bank_mask:0xf bound_ctrl:1
	v_add_f32_dpp v79, v79, v79 row_mirror row_mask:0xf bank_mask:0xf bound_ctrl:1
	v_pk_fma_f32 v[84:85], v[4:5], v[34:35], v[84:85] op_sel:[0,1,0] op_sel_hi:[1,1,1]
	ds_read_b128 v[22:25], v100 offset:4608
	v_pk_fma_f32 v[86:87], v[6:7], v[36:37], v[86:87] op_sel_hi:[1,0,1]
	ds_read_b128 v[26:29], v100 offset:4864
	v_pk_fma_f32 v[88:89], v[8:9], v[36:37], v[88:89] op_sel:[0,1,0] op_sel_hi:[1,1,1]
	v_pk_fma_f32 v[2:3], v[78:79], v[42:43], v[82:83] op_sel_hi:[1,0,1]
	v_pk_fma_f32 v[4:5], v[78:79], v[42:43], v[84:85] op_sel:[0,1,0] op_sel_hi:[1,1,1]
	v_pk_fma_f32 v[6:7], v[78:79], v[44:45], v[86:87] op_sel_hi:[1,0,1]
	v_pk_fma_f32 v[8:9], v[78:79], v[44:45], v[88:89] op_sel:[0,1,0] op_sel_hi:[1,1,1]
	s_waitcnt lgkmcnt(5)
; #define LAS __attribute__((address_space(3)))
; __device__ __forceinline__ void phase_scan(CParams& P, LAS unsigned char* lds) {
;     ...
;             f32x4 Ar0, Ar1, Aw0, Aw1, Ak0, Ak1, Aq0, Aq1, Ab0, Ab1, Br0, Br1, Bw0, Bw1, Bk0, Bk1, Bq0, Bq1, Bb0, Bb1; float Avv, Bvv;
; #pragma unroll 1
;             for (int c = 0; c < NCH; ++c) {
;                 __syncthreads();
;                 const LAS float* base = lf + (c & 1) * BUFF + 8 * oct;
;                 SC_LOAD(A, base);
; #pragma unroll 2
;                 for (int j = 0; j < CH; j += 2) { const LAS float* sp = base + j * STEPF;
;                     SC_LOAD(B, sp + STEPF); SC_STEP(A);
;                     SC_LOAD(A, sp + 2 * STEPF);
;                     SC_STEP(B); }
	v_pk_mul_f32 v[78:79], v[2:3], v[132:133] op_sel_hi:[1,0]
	v_pk_mul_f32 v[92:93], v[2:3], v[46:47] op_sel_hi:[1,0]
	v_pk_fma_f32 v[78:79], v[4:5], v[132:133], v[78:79] op_sel:[0,1,0] op_sel_hi:[1,1,1]
	v_pk_fma_f32 v[92:93], v[4:5], v[46:47], v[92:93] op_sel:[0,1,0] op_sel_hi:[1,1,1]
	v_pk_fma_f32 v[78:79], v[6:7], v[134:135], v[78:79] op_sel_hi:[1,0,1]
	v_pk_fma_f32 v[92:93], v[6:7], v[48:49], v[92:93] op_sel_hi:[1,0,1]
	v_pk_fma_f32 v[78:79], v[8:9], v[134:135], v[78:79] op_sel:[0,1,0] op_sel_hi:[1,1,1]
	v_pk_mul_f32 v[82:83], v[74:75], v[140:141] op_sel_hi:[1,0]
	v_pk_fma_f32 v[92:93], v[8:9], v[48:49], v[92:93] op_sel:[0,1,0] op_sel_hi:[1,1,1]
	v_pk_mul_f32 v[84:85], v[74:75], v[140:141] op_sel:[0,1] op_sel_hi:[1,1]
	v_add_f32_dpp v78, v78, v78 quad_perm:[1,0,3,2] row_mask:0xf bank_mask:0xf bound_ctrl:1
	v_add_f32_dpp v79, v79, v79 quad_perm:[1,0,3,2] row_mask:0xf bank_mask:0xf bound_ctrl:1
	v_pk_mul_f32 v[86:87], v[74:75], v[142:143] op_sel_hi:[1,0]
	ds_read_b128 v[30:33], v100 offset:5120
	v_add_f32_dpp v78, v78, v78 quad_perm:[2,3,0,1] row_mask:0xf bank_mask:0xf bound_ctrl:1
	v_add_f32_dpp v79, v79, v79 quad_perm:[2,3,0,1] row_mask:0xf bank_mask:0xf bound_ctrl:1
	v_pk_mul_f32 v[88:89], v[74:75], v[142:143] op_sel:[0,1] op_sel_hi:[1,1]
	ds_read_b128 v[38:41], v100 offset:5632
	v_add_f32_dpp v78, v78, v78 row_half_mirror row_mask:0xf bank_mask:0xf bound_ctrl:1
	v_add_f32_dpp v79, v79, v79 row_half_mirror row_mask:0xf bank_mask:0xf bound_ctrl:1
	v_pk_fma_f32 v[82:83], v[2:3], v[136:137], v[82:83] op_sel_hi:[1,0,1]
	ds_read_b128 v[34:37], v100 offset:5376
	v_add_f32_dpp v78, v78, v78 row_mirror row_mask:0xf bank_mask:0xf bound_ctrl:1
	v_add_f32_dpp v79, v79, v79 row_mirror row_mask:0xf bank_mask:0xf bound_ctrl:1
	v_pk_fma_f32 v[84:85], v[4:5], v[136:137], v[84:85] op_sel:[0,1,0] op_sel_hi:[1,1,1]
	ds_read_b128 v[42:45], v100 offset:5888
	v_pk_fma_f32 v[86:87], v[6:7], v[138:139], v[86:87] op_sel_hi:[1,0,1]
	ds_read_b128 v[46:49], v100 offset:6144
	v_pk_fma_f32 v[88:89], v[8:9], v[138:139], v[88:89] op_sel:[0,1,0] op_sel_hi:[1,1,1]
	ds_read_b128 v[70:73], v101 offset:32
	v_pk_fma_f32 v[2:3], v[78:79], v[144:145], v[82:83] op_sel_hi:[1,0,1]
	v_pk_fma_f32 v[4:5], v[78:79], v[144:145], v[84:85] op_sel:[0,1,0] op_sel_hi:[1,1,1]
	v_pk_fma_f32 v[6:7], v[78:79], v[146:147], v[86:87] op_sel_hi:[1,0,1]
	v_pk_fma_f32 v[8:9], v[78:79], v[146:147], v[88:89] op_sel:[0,1,0] op_sel_hi:[1,1,1]
	s_waitcnt lgkmcnt(6)
	v_pk_mul_f32 v[78:79], v[2:3], v[10:11] op_sel_hi:[1,0]
	v_pk_mul_f32 v[94:95], v[2:3], v[148:149] op_sel_hi:[1,0]
	v_pk_fma_f32 v[78:79], v[4:5], v[10:11], v[78:79] op_sel:[0,1,0] op_sel_hi:[1,1,1]
	v_pk_fma_f32 v[94:95], v[4:5], v[148:149], v[94:95] op_sel:[0,1,0] op_sel_hi:[1,1,1]
	v_pk_fma_f32 v[78:79], v[6:7], v[12:13], v[78:79] op_sel_hi:[1,0,1]
	v_pk_fma_f32 v[94:95], v[6:7], v[150:151], v[94:95] op_sel_hi:[1,0,1]
	v_pk_fma_f32 v[78:79], v[8:9], v[12:13], v[78:79] op_sel:[0,1,0] op_sel_hi:[1,1,1]
	v_pk_mul_f32 v[82:83], v[76:77], v[18:19] op_sel_hi:[1,0]
	v_pk_fma_f32 v[94:95], v[8:9], v[150:151], v[94:95] op_sel:[0,1,0] op_sel_hi:[1,1,1]
	v_pk_mul_f32 v[84:85], v[76:77], v[18:19] op_sel:[0,1] op_sel_hi:[1,1]
	v_add_f32_dpp v78, v78, v78 quad_perm:[1,0,3,2] row_mask:0xf bank_mask:0xf bound_ctrl:1
	v_add_f32_dpp v79, v79, v79 quad_perm:[1,0,3,2] row_mask:0xf bank_mask:0xf bound_ctrl:1
	v_pk_mul_f32 v[86:87], v[76:77], v[20:21] op_sel_hi:[1,0]
	ds_read_b128 v[132:135], v100 offset:6400
	v_add_f32_dpp v78, v78, v78 quad_perm:[2,3,0,1] row_mask:0xf bank_mask:0xf bound_ctrl:1
	v_add_f32_dpp v79, v79, v79 quad_perm:[2,3,0,1] row_mask:0xf bank_mask:0xf bound_ctrl:1
	v_pk_mul_f32 v[88:89], v[76:77], v[20:21] op_sel:[0,1] op_sel_hi:[1,1]
	ds_read_b128 v[140:143], v100 offset:6912
	v_add_f32_dpp v78, v78, v78 row_half_mirror row_mask:0xf bank_mask:0xf bound_ctrl:1
	v_add_f32_dpp v79, v79, v79 row_half_mirror row_mask:0xf bank_mask:0xf bound_ctrl:1
	v_pk_fma_f32 v[82:83], v[2:3], v[14:15], v[82:83] op_sel_hi:[1,0,1]
	ds_read_b128 v[136:139], v100 offset:6656
	v_add_f32_dpp v78, v78, v78 row_mirror row_mask:0xf bank_mask:0xf bound_ctrl:1
	v_add_f32_dpp v79, v79, v79 row_mirror row_mask:0xf bank_mask:0xf bound_ctrl:1
	v_pk_fma_f32 v[84:85], v[4:5], v[14:15], v[84:85] op_sel:[0,1,0] op_sel_hi:[1,1,1]
	ds_read_b128 v[144:147], v100 offset:7168
	v_pk_fma_f32 v[86:87], v[6:7], v[16:17], v[86:87] op_sel_hi:[1,0,1]
	ds_read_b128 v[148:151], v100 offset:7424
	v_pk_fma_f32 v[88:89], v[8:9], v[16:17], v[88:89] op_sel:[0,1,0] op_sel_hi:[1,1,1]
	v_pk_fma_f32 v[2:3], v[78:79], v[22:23], v[82:83] op_sel_hi:[1,0,1]
	v_pk_fma_f32 v[4:5], v[78:79], v[22:23], v[84:85] op_sel:[0,1,0] op_sel_hi:[1,1,1]
	v_pk_fma_f32 v[6:7], v[78:79], v[24:25], v[86:87] op_sel_hi:[1,0,1]
	v_pk_fma_f32 v[8:9], v[78:79], v[24:25], v[88:89] op_sel:[0,1,0] op_sel_hi:[1,1,1]
	s_waitcnt lgkmcnt(5)
; #define LAS __attribute__((address_space(3)))
; __device__ __forceinline__ void phase_scan(CParams& P, LAS unsigned char* lds) {
;     ...
;             f32x4 Ar0, Ar1, Aw0, Aw1, Ak0, Ak1, Aq0, Aq1, Ab0, Ab1, Br0, Br1, Bw0, Bw1, Bk0, Bk1, Bq0, Bq1, Bb0, Bb1; float Avv, Bvv;
; #pragma unroll 1
;             for (int c = 0; c < NCH; ++c) {
;                 __syncthreads();
;                 const LAS float* base = lf + (c & 1) * BUFF + 8 * oct;
;                 SC_LOAD(A, base);
; #pragma unroll 2
;                 for (int j = 0; j < CH; j += 2) { const LAS float* sp = base + j * STEPF;
;                     SC_LOAD(B, sp + STEPF); SC_STEP(A);
;                     SC_LOAD(A, sp + 2 * STEPF);
;                     SC_STEP(B); }
	v_pk_mul_f32 v[78:79], v[2:3], v[30:31] op_sel_hi:[1,0]
	v_pk_mul_f32 v[96:97], v[2:3], v[26:27] op_sel_hi:[1,0]
	v_pk_fma_f32 v[78:79], v[4:5], v[30:31], v[78:79] op_sel:[0,1,0] op_sel_hi:[1,1,1]
	v_pk_fma_f32 v[96:97], v[4:5], v[26:27], v[96:97] op_sel:[0,1,0] op_sel_hi:[1,1,1]
	v_pk_fma_f32 v[78:79], v[6:7], v[32:33], v[78:79] op_sel_hi:[1,0,1]
	v_pk_fma_f32 v[96:97], v[6:7], v[28:29], v[96:97] op_sel_hi:[1,0,1]
	v_pk_fma_f32 v[78:79], v[8:9], v[32:33], v[78:79] op_sel:[0,1,0] op_sel_hi:[1,1,1]
	v_pk_mul_f32 v[82:83], v[70:71], v[38:39] op_sel_hi:[1,0]
	v_pk_fma_f32 v[96:97], v[8:9], v[28:29], v[96:97] op_sel:[0,1,0] op_sel_hi:[1,1,1]
	v_pk_mul_f32 v[84:85], v[70:71], v[38:39] op_sel:[0,1] op_sel_hi:[1,1]
	v_add_f32_dpp v78, v78, v78 quad_perm:[1,0,3,2] row_mask:0xf bank_mask:0xf bound_ctrl:1
	v_add_f32_dpp v79, v79, v79 quad_perm:[1,0,3,2] row_mask:0xf bank_mask:0xf bound_ctrl:1
	v_pk_mul_f32 v[86:87], v[70:71], v[40:41] op_sel_hi:[1,0]
	ds_read_b128 v[10:13], v100 offset:7680
	v_add_f32_dpp v78, v78, v78 quad_perm:[2,3,0,1] row_mask:0xf bank_mask:0xf bound_ctrl:1
	v_add_f32_dpp v79, v79, v79 quad_perm:[2,3,0,1] row_mask:0xf bank_mask:0xf bound_ctrl:1
	v_pk_mul_f32 v[88:89], v[70:71], v[40:41] op_sel:[0,1] op_sel_hi:[1,1]
	ds_read_b128 v[18:21], v100 offset:8192
	v_add_f32_dpp v78, v78, v78 row_half_mirror row_mask:0xf bank_mask:0xf bound_ctrl:1
	v_add_f32_dpp v79, v79, v79 row_half_mirror row_mask:0xf bank_mask:0xf bound_ctrl:1
	v_pk_fma_f32 v[82:83], v[2:3], v[34:35], v[82:83] op_sel_hi:[1,0,1]
	ds_read_b128 v[14:17], v100 offset:7936
	v_add_f32_dpp v78, v78, v78 row_mirror row_mask:0xf bank_mask:0xf bound_ctrl:1
	v_add_f32_dpp v79, v79, v79 row_mirror row_mask:0xf bank_mask:0xf bound_ctrl:1
	v_pk_fma_f32 v[84:85], v[4:5], v[34:35], v[84:85] op_sel:[0,1,0] op_sel_hi:[1,1,1]
	ds_read_b128 v[22:25], v100 offset:8448
	v_pk_fma_f32 v[86:87], v[6:7], v[36:37], v[86:87] op_sel_hi:[1,0,1]
	ds_read_b128 v[26:29], v100 offset:8704
	v_pk_fma_f32 v[88:89], v[8:9], v[36:37], v[88:89] op_sel:[0,1,0] op_sel_hi:[1,1,1]
	ds_read_b128 v[74:77], v101 offset:48
	v_cndmask_b32_e64 v104, v90, v92, s[50:51]
	v_cndmask_b32_e64 v106, v92, v90, s[50:51]
	v_cndmask_b32_e64 v108, v94, v96, s[50:51]
	v_pk_fma_f32 v[2:3], v[78:79], v[42:43], v[82:83] op_sel_hi:[1,0,1]
	v_pk_fma_f32 v[4:5], v[78:79], v[42:43], v[84:85] op_sel:[0,1,0] op_sel_hi:[1,1,1]
	v_pk_fma_f32 v[6:7], v[78:79], v[44:45], v[86:87] op_sel_hi:[1,0,1]
	v_pk_fma_f32 v[8:9], v[78:79], v[44:45], v[88:89] op_sel:[0,1,0] op_sel_hi:[1,1,1]
	v_cndmask_b32_e64 v110, v96, v94, s[50:51]
	v_cndmask_b32_e64 v105, v91, v93, s[50:51]
	v_cndmask_b32_e64 v107, v93, v91, s[50:51]
	s_waitcnt lgkmcnt(6)
	v_pk_mul_f32 v[78:79], v[2:3], v[132:133] op_sel_hi:[1,0]
	v_pk_mul_f32 v[90:91], v[2:3], v[46:47] op_sel_hi:[1,0]
	v_pk_fma_f32 v[78:79], v[4:5], v[132:133], v[78:79] op_sel:[0,1,0] op_sel_hi:[1,1,1]
	v_pk_fma_f32 v[90:91], v[4:5], v[46:47], v[90:91] op_sel:[0,1,0] op_sel_hi:[1,1,1]
	v_pk_fma_f32 v[78:79], v[6:7], v[134:135], v[78:79] op_sel_hi:[1,0,1]
	v_pk_fma_f32 v[90:91], v[6:7], v[48:49], v[90:91] op_sel_hi:[1,0,1]
	v_pk_fma_f32 v[78:79], v[8:9], v[134:135], v[78:79] op_sel:[0,1,0] op_sel_hi:[1,1,1]
	v_pk_mul_f32 v[82:83], v[72:73], v[140:141] op_sel_hi:[1,0]
	v_pk_fma_f32 v[90:91], v[8:9], v[48:49], v[90:91] op_sel:[0,1,0] op_sel_hi:[1,1,1]
	v_pk_mul_f32 v[84:85], v[72:73], v[140:141] op_sel:[0,1] op_sel_hi:[1,1]
	v_add_f32_dpp v78, v78, v78 quad_perm:[1,0,3,2] row_mask:0xf bank_mask:0xf bound_ctrl:1
	v_add_f32_dpp v79, v79, v79 quad_perm:[1,0,3,2] row_mask:0xf bank_mask:0xf bound_ctrl:1
	v_pk_mul_f32 v[86:87], v[72:73], v[142:143] op_sel_hi:[1,0]
	ds_read_b128 v[30:33], v100 offset:8960
	v_add_f32_dpp v78, v78, v78 quad_perm:[2,3,0,1] row_mask:0xf bank_mask:0xf bound_ctrl:1
	v_add_f32_dpp v79, v79, v79 quad_perm:[2,3,0,1] row_mask:0xf bank_mask:0xf bound_ctrl:1
	v_pk_mul_f32 v[88:89], v[72:73], v[142:143] op_sel:[0,1] op_sel_hi:[1,1]
	ds_read_b128 v[38:41], v100 offset:9472
	v_add_f32_dpp v78, v78, v78 row_half_mirror row_mask:0xf bank_mask:0xf bound_ctrl:1
	v_add_f32_dpp v79, v79, v79 row_half_mirror row_mask:0xf bank_mask:0xf bound_ctrl:1
	v_pk_fma_f32 v[82:83], v[2:3], v[136:137], v[82:83] op_sel_hi:[1,0,1]
	ds_read_b128 v[34:37], v100 offset:9216
	v_add_f32_dpp v78, v78, v78 row_mirror row_mask:0xf bank_mask:0xf bound_ctrl:1
	v_add_f32_dpp v79, v79, v79 row_mirror row_mask:0xf bank_mask:0xf bound_ctrl:1
	v_pk_fma_f32 v[84:85], v[4:5], v[136:137], v[84:85] op_sel:[0,1,0] op_sel_hi:[1,1,1]
	ds_read_b128 v[42:45], v100 offset:9728
	v_pk_fma_f32 v[86:87], v[6:7], v[138:139], v[86:87] op_sel_hi:[1,0,1]
	ds_read_b128 v[46:49], v100 offset:9984
	v_pk_fma_f32 v[88:89], v[8:9], v[138:139], v[88:89] op_sel:[0,1,0] op_sel_hi:[1,1,1]
	v_cndmask_b32_e64 v109, v95, v97, s[50:51]
	v_cndmask_b32_e64 v111, v97, v95, s[50:51]
	v_add_f32_dpp v112, v106, v104 quad_perm:[1,0,3,2] row_mask:0xf bank_mask:0xf bound_ctrl:1
	v_pk_fma_f32 v[2:3], v[78:79], v[144:145], v[82:83] op_sel_hi:[1,0,1]
	v_pk_fma_f32 v[4:5], v[78:79], v[144:145], v[84:85] op_sel:[0,1,0] op_sel_hi:[1,1,1]
	v_pk_fma_f32 v[6:7], v[78:79], v[146:147], v[86:87] op_sel_hi:[1,0,1]
	v_pk_fma_f32 v[8:9], v[78:79], v[146:147], v[88:89] op_sel:[0,1,0] op_sel_hi:[1,1,1]
	v_add_f32_dpp v114, v110, v108 quad_perm:[1,0,3,2] row_mask:0xf bank_mask:0xf bound_ctrl:1
	v_add_f32_dpp v113, v107, v105 quad_perm:[1,0,3,2] row_mask:0xf bank_mask:0xf bound_ctrl:1
	v_add_f32_dpp v115, v111, v109 quad_perm:[1,0,3,2] row_mask:0xf bank_mask:0xf bound_ctrl:1
	s_waitcnt lgkmcnt(5)
; #define LAS __attribute__((address_space(3)))
; __device__ __forceinline__ void phase_scan(CParams& P, LAS unsigned char* lds) {
;     ...
;             f32x4 Ar0, Ar1, Aw0, Aw1, Ak0, Ak1, Aq0, Aq1, Ab0, Ab1, Br0, Br1, Bw0, Bw1, Bk0, Bk1, Bq0, Bq1, Bb0, Bb1; float Avv, Bvv;
; #pragma unroll 1
;             for (int c = 0; c < NCH; ++c) {
;                 __syncthreads();
;                 const LAS float* base = lf + (c & 1) * BUFF + 8 * oct;
;                 SC_LOAD(A, base);
; #pragma unroll 2
;                 for (int j = 0; j < CH; j += 2) { const LAS float* sp = base + j * STEPF;
;                     SC_LOAD(B, sp + STEPF); SC_STEP(A);
;                     SC_LOAD(A, sp + 2 * STEPF);
;                     SC_STEP(B); }
	v_pk_mul_f32 v[78:79], v[2:3], v[10:11] op_sel_hi:[1,0]
	v_pk_mul_f32 v[92:93], v[2:3], v[148:149] op_sel_hi:[1,0]
	v_pk_fma_f32 v[78:79], v[4:5], v[10:11], v[78:79] op_sel:[0,1,0] op_sel_hi:[1,1,1]
	v_pk_fma_f32 v[92:93], v[4:5], v[148:149], v[92:93] op_sel:[0,1,0] op_sel_hi:[1,1,1]
	v_pk_fma_f32 v[78:79], v[6:7], v[12:13], v[78:79] op_sel_hi:[1,0,1]
	v_pk_fma_f32 v[92:93], v[6:7], v[150:151], v[92:93] op_sel_hi:[1,0,1]
	v_pk_fma_f32 v[78:79], v[8:9], v[12:13], v[78:79] op_sel:[0,1,0] op_sel_hi:[1,1,1]
	v_pk_mul_f32 v[82:83], v[74:75], v[18:19] op_sel_hi:[1,0]
	v_pk_fma_f32 v[92:93], v[8:9], v[150:151], v[92:93] op_sel:[0,1,0] op_sel_hi:[1,1,1]
	v_pk_mul_f32 v[84:85], v[74:75], v[18:19] op_sel:[0,1] op_sel_hi:[1,1]
	v_add_f32_dpp v78, v78, v78 quad_perm:[1,0,3,2] row_mask:0xf bank_mask:0xf bound_ctrl:1
	v_add_f32_dpp v79, v79, v79 quad_perm:[1,0,3,2] row_mask:0xf bank_mask:0xf bound_ctrl:1
	v_pk_mul_f32 v[86:87], v[74:75], v[20:21] op_sel_hi:[1,0]
	ds_read_b128 v[132:135], v100 offset:10240
	v_add_f32_dpp v78, v78, v78 quad_perm:[2,3,0,1] row_mask:0xf bank_mask:0xf bound_ctrl:1
	v_add_f32_dpp v79, v79, v79 quad_perm:[2,3,0,1] row_mask:0xf bank_mask:0xf bound_ctrl:1
	v_pk_mul_f32 v[88:89], v[74:75], v[20:21] op_sel:[0,1] op_sel_hi:[1,1]
	ds_read_b128 v[140:143], v100 offset:10752
	v_add_f32_dpp v78, v78, v78 row_half_mirror row_mask:0xf bank_mask:0xf bound_ctrl:1
	v_add_f32_dpp v79, v79, v79 row_half_mirror row_mask:0xf bank_mask:0xf bound_ctrl:1
	v_pk_fma_f32 v[82:83], v[2:3], v[14:15], v[82:83] op_sel_hi:[1,0,1]
	ds_read_b128 v[136:139], v100 offset:10496
	v_add_f32_dpp v78, v78, v78 row_mirror row_mask:0xf bank_mask:0xf bound_ctrl:1
	v_add_f32_dpp v79, v79, v79 row_mirror row_mask:0xf bank_mask:0xf bound_ctrl:1
	v_pk_fma_f32 v[84:85], v[4:5], v[14:15], v[84:85] op_sel:[0,1,0] op_sel_hi:[1,1,1]
	ds_read_b128 v[144:147], v100 offset:11008
	v_pk_fma_f32 v[86:87], v[6:7], v[16:17], v[86:87] op_sel_hi:[1,0,1]
	ds_read_b128 v[148:151], v100 offset:11264
	v_pk_fma_f32 v[88:89], v[8:9], v[16:17], v[88:89] op_sel:[0,1,0] op_sel_hi:[1,1,1]
	ds_read_b128 v[70:73], v101 offset:64
	v_cndmask_b32_e64 v116, v112, v114, s[52:53]
	v_cndmask_b32_e64 v118, v114, v112, s[52:53]
	v_cndmask_b32_e64 v117, v113, v115, s[52:53]
	v_pk_fma_f32 v[2:3], v[78:79], v[22:23], v[82:83] op_sel_hi:[1,0,1]
	v_pk_fma_f32 v[4:5], v[78:79], v[22:23], v[84:85] op_sel:[0,1,0] op_sel_hi:[1,1,1]
	v_pk_fma_f32 v[6:7], v[78:79], v[24:25], v[86:87] op_sel_hi:[1,0,1]
	v_pk_fma_f32 v[8:9], v[78:79], v[24:25], v[88:89] op_sel:[0,1,0] op_sel_hi:[1,1,1]
	v_cndmask_b32_e64 v119, v115, v113, s[52:53]
	v_add_f32_dpp v120, v118, v116 quad_perm:[2,3,0,1] row_mask:0xf bank_mask:0xf bound_ctrl:1
	s_nop 0
	v_add_f32_dpp v121, v119, v117 quad_perm:[2,3,0,1] row_mask:0xf bank_mask:0xf bound_ctrl:1
	s_waitcnt lgkmcnt(6)
	v_pk_mul_f32 v[78:79], v[2:3], v[30:31] op_sel_hi:[1,0]
	v_pk_mul_f32 v[94:95], v[2:3], v[26:27] op_sel_hi:[1,0]
	v_pk_fma_f32 v[78:79], v[4:5], v[30:31], v[78:79] op_sel:[0,1,0] op_sel_hi:[1,1,1]
	v_pk_fma_f32 v[94:95], v[4:5], v[26:27], v[94:95] op_sel:[0,1,0] op_sel_hi:[1,1,1]
	v_pk_fma_f32 v[78:79], v[6:7], v[32:33], v[78:79] op_sel_hi:[1,0,1]
	v_pk_fma_f32 v[94:95], v[6:7], v[28:29], v[94:95] op_sel_hi:[1,0,1]
	v_pk_fma_f32 v[78:79], v[8:9], v[32:33], v[78:79] op_sel:[0,1,0] op_sel_hi:[1,1,1]
	v_pk_mul_f32 v[82:83], v[76:77], v[38:39] op_sel_hi:[1,0]
	v_pk_fma_f32 v[94:95], v[8:9], v[28:29], v[94:95] op_sel:[0,1,0] op_sel_hi:[1,1,1]
	v_pk_mul_f32 v[84:85], v[76:77], v[38:39] op_sel:[0,1] op_sel_hi:[1,1]
	v_add_f32_dpp v78, v78, v78 quad_perm:[1,0,3,2] row_mask:0xf bank_mask:0xf bound_ctrl:1
	v_add_f32_dpp v79, v79, v79 quad_perm:[1,0,3,2] row_mask:0xf bank_mask:0xf bound_ctrl:1
	v_pk_mul_f32 v[86:87], v[76:77], v[40:41] op_sel_hi:[1,0]
	ds_read_b128 v[10:13], v100 offset:11520
	v_add_f32_dpp v78, v78, v78 quad_perm:[2,3,0,1] row_mask:0xf bank_mask:0xf bound_ctrl:1
	v_add_f32_dpp v79, v79, v79 quad_perm:[2,3,0,1] row_mask:0xf bank_mask:0xf bound_ctrl:1
	v_pk_mul_f32 v[88:89], v[76:77], v[40:41] op_sel:[0,1] op_sel_hi:[1,1]
	ds_read_b128 v[18:21], v100 offset:12032
	v_add_f32_dpp v78, v78, v78 row_half_mirror row_mask:0xf bank_mask:0xf bound_ctrl:1
	v_add_f32_dpp v79, v79, v79 row_half_mirror row_mask:0xf bank_mask:0xf bound_ctrl:1
	v_pk_fma_f32 v[82:83], v[2:3], v[34:35], v[82:83] op_sel_hi:[1,0,1]
	ds_read_b128 v[14:17], v100 offset:11776
	v_add_f32_dpp v78, v78, v78 row_mirror row_mask:0xf bank_mask:0xf bound_ctrl:1
	v_add_f32_dpp v79, v79, v79 row_mirror row_mask:0xf bank_mask:0xf bound_ctrl:1
	v_pk_fma_f32 v[84:85], v[4:5], v[34:35], v[84:85] op_sel:[0,1,0] op_sel_hi:[1,1,1]
	ds_read_b128 v[22:25], v100 offset:12288
	v_pk_fma_f32 v[86:87], v[6:7], v[36:37], v[86:87] op_sel_hi:[1,0,1]
	ds_read_b128 v[26:29], v100 offset:12544
	v_pk_fma_f32 v[88:89], v[8:9], v[36:37], v[88:89] op_sel:[0,1,0] op_sel_hi:[1,1,1]
	v_add_f32_dpp v120, v120, v120 row_ror:4 row_mask:0xf bank_mask:0xf bound_ctrl:1
	v_add_f32_dpp v121, v121, v121 row_ror:4 row_mask:0xf bank_mask:0xf bound_ctrl:1
	s_nop 0
	v_add_f32_dpp v120, v120, v120 row_ror:8 row_mask:0xf bank_mask:0xf bound_ctrl:1
	v_pk_fma_f32 v[2:3], v[78:79], v[42:43], v[82:83] op_sel_hi:[1,0,1]
	v_pk_fma_f32 v[4:5], v[78:79], v[42:43], v[84:85] op_sel:[0,1,0] op_sel_hi:[1,1,1]
	v_pk_fma_f32 v[6:7], v[78:79], v[44:45], v[86:87] op_sel_hi:[1,0,1]
	v_pk_fma_f32 v[8:9], v[78:79], v[44:45], v[88:89] op_sel:[0,1,0] op_sel_hi:[1,1,1]
	v_add_f32_dpp v121, v121, v121 row_ror:8 row_mask:0xf bank_mask:0xf bound_ctrl:1
	global_store_dwordx2 v102, v[120:121], s[10:11]
	v_add_u32_e32 v102, s13, v102
	s_waitcnt lgkmcnt(5)
; #define LAS __attribute__((address_space(3)))
; __device__ __forceinline__ void phase_scan(CParams& P, LAS unsigned char* lds) {
;     ...
;             f32x4 Ar0, Ar1, Aw0, Aw1, Ak0, Ak1, Aq0, Aq1, Ab0, Ab1, Br0, Br1, Bw0, Bw1, Bk0, Bk1, Bq0, Bq1, Bb0, Bb1; float Avv, Bvv;
; #pragma unroll 1
;             for (int c = 0; c < NCH; ++c) {
;                 __syncthreads();
;                 const LAS float* base = lf + (c & 1) * BUFF + 8 * oct;
;                 SC_LOAD(A, base);
; #pragma unroll 2
;                 for (int j = 0; j < CH; j += 2) { const LAS float* sp = base + j * STEPF;
;                     SC_LOAD(B, sp + STEPF); SC_STEP(A);
;                     SC_LOAD(A, sp + 2 * STEPF);
;                     SC_STEP(B); }
	v_pk_mul_f32 v[78:79], v[2:3], v[132:133] op_sel_hi:[1,0]
	v_pk_mul_f32 v[96:97], v[2:3], v[46:47] op_sel_hi:[1,0]
	v_pk_fma_f32 v[78:79], v[4:5], v[132:133], v[78:79] op_sel:[0,1,0] op_sel_hi:[1,1,1]
	v_pk_fma_f32 v[96:97], v[4:5], v[46:47], v[96:97] op_sel:[0,1,0] op_sel_hi:[1,1,1]
	v_pk_fma_f32 v[78:79], v[6:7], v[134:135], v[78:79] op_sel_hi:[1,0,1]
	v_pk_fma_f32 v[96:97], v[6:7], v[48:49], v[96:97] op_sel_hi:[1,0,1]
	v_pk_fma_f32 v[78:79], v[8:9], v[134:135], v[78:79] op_sel:[0,1,0] op_sel_hi:[1,1,1]
	v_pk_mul_f32 v[82:83], v[70:71], v[140:141] op_sel_hi:[1,0]
	v_pk_fma_f32 v[96:97], v[8:9], v[48:49], v[96:97] op_sel:[0,1,0] op_sel_hi:[1,1,1]
	v_pk_mul_f32 v[84:85], v[70:71], v[140:141] op_sel:[0,1] op_sel_hi:[1,1]
	v_add_f32_dpp v78, v78, v78 quad_perm:[1,0,3,2] row_mask:0xf bank_mask:0xf bound_ctrl:1
	v_add_f32_dpp v79, v79, v79 quad_perm:[1,0,3,2] row_mask:0xf bank_mask:0xf bound_ctrl:1
	v_pk_mul_f32 v[86:87], v[70:71], v[142:143] op_sel_hi:[1,0]
	ds_read_b128 v[30:33], v100 offset:12800
	v_add_f32_dpp v78, v78, v78 quad_perm:[2,3,0,1] row_mask:0xf bank_mask:0xf bound_ctrl:1
	v_add_f32_dpp v79, v79, v79 quad_perm:[2,3,0,1] row_mask:0xf bank_mask:0xf bound_ctrl:1
	v_pk_mul_f32 v[88:89], v[70:71], v[142:143] op_sel:[0,1] op_sel_hi:[1,1]
	ds_read_b128 v[38:41], v100 offset:13312
	v_add_f32_dpp v78, v78, v78 row_half_mirror row_mask:0xf bank_mask:0xf bound_ctrl:1
	v_add_f32_dpp v79, v79, v79 row_half_mirror row_mask:0xf bank_mask:0xf bound_ctrl:1
	v_pk_fma_f32 v[82:83], v[2:3], v[136:137], v[82:83] op_sel_hi:[1,0,1]
	ds_read_b128 v[34:37], v100 offset:13056
	v_add_f32_dpp v78, v78, v78 row_mirror row_mask:0xf bank_mask:0xf bound_ctrl:1
	v_add_f32_dpp v79, v79, v79 row_mirror row_mask:0xf bank_mask:0xf bound_ctrl:1
	v_pk_fma_f32 v[84:85], v[4:5], v[136:137], v[84:85] op_sel:[0,1,0] op_sel_hi:[1,1,1]
	ds_read_b128 v[42:45], v100 offset:13568
	v_pk_fma_f32 v[86:87], v[6:7], v[138:139], v[86:87] op_sel_hi:[1,0,1]
	ds_read_b128 v[46:49], v100 offset:13824
	v_pk_fma_f32 v[88:89], v[8:9], v[138:139], v[88:89] op_sel:[0,1,0] op_sel_hi:[1,1,1]
	ds_read_b128 v[74:77], v101 offset:80
	v_cndmask_b32_e64 v104, v90, v92, s[50:51]
	v_cndmask_b32_e64 v106, v92, v90, s[50:51]
	v_cndmask_b32_e64 v108, v94, v96, s[50:51]
	v_pk_fma_f32 v[2:3], v[78:79], v[144:145], v[82:83] op_sel_hi:[1,0,1]
	v_pk_fma_f32 v[4:5], v[78:79], v[144:145], v[84:85] op_sel:[0,1,0] op_sel_hi:[1,1,1]
	v_pk_fma_f32 v[6:7], v[78:79], v[146:147], v[86:87] op_sel_hi:[1,0,1]
	v_pk_fma_f32 v[8:9], v[78:79], v[146:147], v[88:89] op_sel:[0,1,0] op_sel_hi:[1,1,1]
	v_cndmask_b32_e64 v110, v96, v94, s[50:51]
	v_cndmask_b32_e64 v105, v91, v93, s[50:51]
	v_cndmask_b32_e64 v107, v93, v91, s[50:51]
	s_waitcnt lgkmcnt(6)
	v_pk_mul_f32 v[78:79], v[2:3], v[10:11] op_sel_hi:[1,0]
	v_pk_mul_f32 v[90:91], v[2:3], v[148:149] op_sel_hi:[1,0]
	v_pk_fma_f32 v[78:79], v[4:5], v[10:11], v[78:79] op_sel:[0,1,0] op_sel_hi:[1,1,1]
	v_pk_fma_f32 v[90:91], v[4:5], v[148:149], v[90:91] op_sel:[0,1,0] op_sel_hi:[1,1,1]
	v_pk_fma_f32 v[78:79], v[6:7], v[12:13], v[78:79] op_sel_hi:[1,0,1]
	v_pk_fma_f32 v[90:91], v[6:7], v[150:151], v[90:91] op_sel_hi:[1,0,1]
	v_pk_fma_f32 v[78:79], v[8:9], v[12:13], v[78:79] op_sel:[0,1,0] op_sel_hi:[1,1,1]
	v_pk_mul_f32 v[82:83], v[72:73], v[18:19] op_sel_hi:[1,0]
	v_pk_fma_f32 v[90:91], v[8:9], v[150:151], v[90:91] op_sel:[0,1,0] op_sel_hi:[1,1,1]
	v_pk_mul_f32 v[84:85], v[72:73], v[18:19] op_sel:[0,1] op_sel_hi:[1,1]
	v_add_f32_dpp v78, v78, v78 quad_perm:[1,0,3,2] row_mask:0xf bank_mask:0xf bound_ctrl:1
	v_add_f32_dpp v79, v79, v79 quad_perm:[1,0,3,2] row_mask:0xf bank_mask:0xf bound_ctrl:1
	v_pk_mul_f32 v[86:87], v[72:73], v[20:21] op_sel_hi:[1,0]
	ds_read_b128 v[132:135], v100 offset:14080
	v_add_f32_dpp v78, v78, v78 quad_perm:[2,3,0,1] row_mask:0xf bank_mask:0xf bound_ctrl:1
	v_add_f32_dpp v79, v79, v79 quad_perm:[2,3,0,1] row_mask:0xf bank_mask:0xf bound_ctrl:1
	v_pk_mul_f32 v[88:89], v[72:73], v[20:21] op_sel:[0,1] op_sel_hi:[1,1]
	ds_read_b128 v[140:143], v100 offset:14592
	v_add_f32_dpp v78, v78, v78 row_half_mirror row_mask:0xf bank_mask:0xf bound_ctrl:1
	v_add_f32_dpp v79, v79, v79 row_half_mirror row_mask:0xf bank_mask:0xf bound_ctrl:1
	v_pk_fma_f32 v[82:83], v[2:3], v[14:15], v[82:83] op_sel_hi:[1,0,1]
	ds_read_b128 v[136:139], v100 offset:14336
	v_add_f32_dpp v78, v78, v78 row_mirror row_mask:0xf bank_mask:0xf bound_ctrl:1
	v_add_f32_dpp v79, v79, v79 row_mirror row_mask:0xf bank_mask:0xf bound_ctrl:1
	v_pk_fma_f32 v[84:85], v[4:5], v[14:15], v[84:85] op_sel:[0,1,0] op_sel_hi:[1,1,1]
	ds_read_b128 v[144:147], v100 offset:14848
	v_pk_fma_f32 v[86:87], v[6:7], v[16:17], v[86:87] op_sel_hi:[1,0,1]
	ds_read_b128 v[148:151], v100 offset:15104
	v_pk_fma_f32 v[88:89], v[8:9], v[16:17], v[88:89] op_sel:[0,1,0] op_sel_hi:[1,1,1]
	v_cndmask_b32_e64 v109, v95, v97, s[50:51]
	v_cndmask_b32_e64 v111, v97, v95, s[50:51]
	v_add_f32_dpp v112, v106, v104 quad_perm:[1,0,3,2] row_mask:0xf bank_mask:0xf bound_ctrl:1
	v_pk_fma_f32 v[2:3], v[78:79], v[22:23], v[82:83] op_sel_hi:[1,0,1]
	v_pk_fma_f32 v[4:5], v[78:79], v[22:23], v[84:85] op_sel:[0,1,0] op_sel_hi:[1,1,1]
	v_pk_fma_f32 v[6:7], v[78:79], v[24:25], v[86:87] op_sel_hi:[1,0,1]
	v_pk_fma_f32 v[8:9], v[78:79], v[24:25], v[88:89] op_sel:[0,1,0] op_sel_hi:[1,1,1]
	v_add_f32_dpp v114, v110, v108 quad_perm:[1,0,3,2] row_mask:0xf bank_mask:0xf bound_ctrl:1
	v_add_f32_dpp v113, v107, v105 quad_perm:[1,0,3,2] row_mask:0xf bank_mask:0xf bound_ctrl:1
	v_add_f32_dpp v115, v111, v109 quad_perm:[1,0,3,2] row_mask:0xf bank_mask:0xf bound_ctrl:1
	s_waitcnt lgkmcnt(5)
; #define LAS __attribute__((address_space(3)))
; __device__ __forceinline__ void phase_scan(CParams& P, LAS unsigned char* lds) {
;     ...
;             f32x4 Ar0, Ar1, Aw0, Aw1, Ak0, Ak1, Aq0, Aq1, Ab0, Ab1, Br0, Br1, Bw0, Bw1, Bk0, Bk1, Bq0, Bq1, Bb0, Bb1; float Avv, Bvv;
; #pragma unroll 1
;             for (int c = 0; c < NCH; ++c) {
;                 __syncthreads();
;                 const LAS float* base = lf + (c & 1) * BUFF + 8 * oct;
;                 SC_LOAD(A, base);
; #pragma unroll 2
;                 for (int j = 0; j < CH; j += 2) { const LAS float* sp = base + j * STEPF;
;                     SC_LOAD(B, sp + STEPF); SC_STEP(A);
;                     SC_LOAD(A, sp + 2 * STEPF);
;                     SC_STEP(B); }
	v_pk_mul_f32 v[78:79], v[2:3], v[30:31] op_sel_hi:[1,0]
	v_pk_mul_f32 v[92:93], v[2:3], v[26:27] op_sel_hi:[1,0]
	v_pk_fma_f32 v[78:79], v[4:5], v[30:31], v[78:79] op_sel:[0,1,0] op_sel_hi:[1,1,1]
	v_pk_fma_f32 v[92:93], v[4:5], v[26:27], v[92:93] op_sel:[0,1,0] op_sel_hi:[1,1,1]
	v_pk_fma_f32 v[78:79], v[6:7], v[32:33], v[78:79] op_sel_hi:[1,0,1]
	v_pk_fma_f32 v[92:93], v[6:7], v[28:29], v[92:93] op_sel_hi:[1,0,1]
	v_pk_fma_f32 v[78:79], v[8:9], v[32:33], v[78:79] op_sel:[0,1,0] op_sel_hi:[1,1,1]
	v_pk_mul_f32 v[82:83], v[74:75], v[38:39] op_sel_hi:[1,0]
	v_pk_fma_f32 v[92:93], v[8:9], v[28:29], v[92:93] op_sel:[0,1,0] op_sel_hi:[1,1,1]
	v_pk_mul_f32 v[84:85], v[74:75], v[38:39] op_sel:[0,1] op_sel_hi:[1,1]
	v_add_f32_dpp v78, v78, v78 quad_perm:[1,0,3,2] row_mask:0xf bank_mask:0xf bound_ctrl:1
	v_add_f32_dpp v79, v79, v79 quad_perm:[1,0,3,2] row_mask:0xf bank_mask:0xf bound_ctrl:1
	v_pk_mul_f32 v[86:87], v[74:75], v[40:41] op_sel_hi:[1,0]
	ds_read_b128 v[10:13], v100 offset:15360
	v_add_f32_dpp v78, v78, v78 quad_perm:[2,3,0,1] row_mask:0xf bank_mask:0xf bound_ctrl:1
	v_add_f32_dpp v79, v79, v79 quad_perm:[2,3,0,1] row_mask:0xf bank_mask:0xf bound_ctrl:1
	v_pk_mul_f32 v[88:89], v[74:75], v[40:41] op_sel:[0,1] op_sel_hi:[1,1]
	ds_read_b128 v[18:21], v100 offset:15872
	v_add_f32_dpp v78, v78, v78 row_half_mirror row_mask:0xf bank_mask:0xf bound_ctrl:1
	v_add_f32_dpp v79, v79, v79 row_half_mirror row_mask:0xf bank_mask:0xf bound_ctrl:1
	v_pk_fma_f32 v[82:83], v[2:3], v[34:35], v[82:83] op_sel_hi:[1,0,1]
	ds_read_b128 v[14:17], v100 offset:15616
	v_add_f32_dpp v78, v78, v78 row_mirror row_mask:0xf bank_mask:0xf bound_ctrl:1
	v_add_f32_dpp v79, v79, v79 row_mirror row_mask:0xf bank_mask:0xf bound_ctrl:1
	v_pk_fma_f32 v[84:85], v[4:5], v[34:35], v[84:85] op_sel:[0,1,0] op_sel_hi:[1,1,1]
	ds_read_b128 v[22:25], v100 offset:16128
	v_pk_fma_f32 v[86:87], v[6:7], v[36:37], v[86:87] op_sel_hi:[1,0,1]
	ds_read_b128 v[26:29], v100 offset:16384
	v_pk_fma_f32 v[88:89], v[8:9], v[36:37], v[88:89] op_sel:[0,1,0] op_sel_hi:[1,1,1]
	ds_read_b128 v[70:73], v101 offset:96
	v_cndmask_b32_e64 v116, v112, v114, s[52:53]
	v_cndmask_b32_e64 v118, v114, v112, s[52:53]
	v_cndmask_b32_e64 v117, v113, v115, s[52:53]
	v_pk_fma_f32 v[2:3], v[78:79], v[42:43], v[82:83] op_sel_hi:[1,0,1]
	v_pk_fma_f32 v[4:5], v[78:79], v[42:43], v[84:85] op_sel:[0,1,0] op_sel_hi:[1,1,1]
	v_pk_fma_f32 v[6:7], v[78:79], v[44:45], v[86:87] op_sel_hi:[1,0,1]
	v_pk_fma_f32 v[8:9], v[78:79], v[44:45], v[88:89] op_sel:[0,1,0] op_sel_hi:[1,1,1]
	v_cndmask_b32_e64 v119, v115, v113, s[52:53]
	v_add_f32_dpp v120, v118, v116 quad_perm:[2,3,0,1] row_mask:0xf bank_mask:0xf bound_ctrl:1
	s_nop 0
	v_add_f32_dpp v121, v119, v117 quad_perm:[2,3,0,1] row_mask:0xf bank_mask:0xf bound_ctrl:1
	s_waitcnt lgkmcnt(6)
	v_pk_mul_f32 v[78:79], v[2:3], v[132:133] op_sel_hi:[1,0]
	v_pk_mul_f32 v[94:95], v[2:3], v[46:47] op_sel_hi:[1,0]
	v_pk_fma_f32 v[78:79], v[4:5], v[132:133], v[78:79] op_sel:[0,1,0] op_sel_hi:[1,1,1]
	v_pk_fma_f32 v[94:95], v[4:5], v[46:47], v[94:95] op_sel:[0,1,0] op_sel_hi:[1,1,1]
	v_pk_fma_f32 v[78:79], v[6:7], v[134:135], v[78:79] op_sel_hi:[1,0,1]
	v_pk_fma_f32 v[94:95], v[6:7], v[48:49], v[94:95] op_sel_hi:[1,0,1]
	v_pk_fma_f32 v[78:79], v[8:9], v[134:135], v[78:79] op_sel:[0,1,0] op_sel_hi:[1,1,1]
	v_pk_mul_f32 v[82:83], v[76:77], v[140:141] op_sel_hi:[1,0]
	v_pk_fma_f32 v[94:95], v[8:9], v[48:49], v[94:95] op_sel:[0,1,0] op_sel_hi:[1,1,1]
	v_pk_mul_f32 v[84:85], v[76:77], v[140:141] op_sel:[0,1] op_sel_hi:[1,1]
	v_add_f32_dpp v78, v78, v78 quad_perm:[1,0,3,2] row_mask:0xf bank_mask:0xf bound_ctrl:1
	v_add_f32_dpp v79, v79, v79 quad_perm:[1,0,3,2] row_mask:0xf bank_mask:0xf bound_ctrl:1
	v_pk_mul_f32 v[86:87], v[76:77], v[142:143] op_sel_hi:[1,0]
	ds_read_b128 v[30:33], v100 offset:16640
	v_add_f32_dpp v78, v78, v78 quad_perm:[2,3,0,1] row_mask:0xf bank_mask:0xf bound_ctrl:1
	v_add_f32_dpp v79, v79, v79 quad_perm:[2,3,0,1] row_mask:0xf bank_mask:0xf bound_ctrl:1
	v_pk_mul_f32 v[88:89], v[76:77], v[142:143] op_sel:[0,1] op_sel_hi:[1,1]
	ds_read_b128 v[38:41], v100 offset:17152
	v_add_f32_dpp v78, v78, v78 row_half_mirror row_mask:0xf bank_mask:0xf bound_ctrl:1
	v_add_f32_dpp v79, v79, v79 row_half_mirror row_mask:0xf bank_mask:0xf bound_ctrl:1
	v_pk_fma_f32 v[82:83], v[2:3], v[136:137], v[82:83] op_sel_hi:[1,0,1]
	ds_read_b128 v[34:37], v100 offset:16896
	v_add_f32_dpp v78, v78, v78 row_mirror row_mask:0xf bank_mask:0xf bound_ctrl:1
	v_add_f32_dpp v79, v79, v79 row_mirror row_mask:0xf bank_mask:0xf bound_ctrl:1
	v_pk_fma_f32 v[84:85], v[4:5], v[136:137], v[84:85] op_sel:[0,1,0] op_sel_hi:[1,1,1]
	ds_read_b128 v[42:45], v100 offset:17408
	v_pk_fma_f32 v[86:87], v[6:7], v[138:139], v[86:87] op_sel_hi:[1,0,1]
	ds_read_b128 v[46:49], v100 offset:17664
	v_pk_fma_f32 v[88:89], v[8:9], v[138:139], v[88:89] op_sel:[0,1,0] op_sel_hi:[1,1,1]
	v_add_f32_dpp v120, v120, v120 row_ror:4 row_mask:0xf bank_mask:0xf bound_ctrl:1
	v_add_f32_dpp v121, v121, v121 row_ror:4 row_mask:0xf bank_mask:0xf bound_ctrl:1
	s_nop 0
	v_add_f32_dpp v120, v120, v120 row_ror:8 row_mask:0xf bank_mask:0xf bound_ctrl:1
	v_pk_fma_f32 v[2:3], v[78:79], v[144:145], v[82:83] op_sel_hi:[1,0,1]
	v_pk_fma_f32 v[4:5], v[78:79], v[144:145], v[84:85] op_sel:[0,1,0] op_sel_hi:[1,1,1]
	v_pk_fma_f32 v[6:7], v[78:79], v[146:147], v[86:87] op_sel_hi:[1,0,1]
	v_pk_fma_f32 v[8:9], v[78:79], v[146:147], v[88:89] op_sel:[0,1,0] op_sel_hi:[1,1,1]
	v_add_f32_dpp v121, v121, v121 row_ror:8 row_mask:0xf bank_mask:0xf bound_ctrl:1
	global_store_dwordx2 v102, v[120:121], s[10:11]
	v_add_u32_e32 v102, s13, v102
	s_waitcnt lgkmcnt(5)
; #define LAS __attribute__((address_space(3)))
; __device__ __forceinline__ void phase_scan(CParams& P, LAS unsigned char* lds) {
;     ...
;             f32x4 Ar0, Ar1, Aw0, Aw1, Ak0, Ak1, Aq0, Aq1, Ab0, Ab1, Br0, Br1, Bw0, Bw1, Bk0, Bk1, Bq0, Bq1, Bb0, Bb1; float Avv, Bvv;
; #pragma unroll 1
;             for (int c = 0; c < NCH; ++c) {
;                 __syncthreads();
;                 const LAS float* base = lf + (c & 1) * BUFF + 8 * oct;
;                 SC_LOAD(A, base);
; #pragma unroll 2
;                 for (int j = 0; j < CH; j += 2) { const LAS float* sp = base + j * STEPF;
;                     SC_LOAD(B, sp + STEPF); SC_STEP(A);
;                     SC_LOAD(A, sp + 2 * STEPF);
;                     SC_STEP(B); }
	v_pk_mul_f32 v[78:79], v[2:3], v[10:11] op_sel_hi:[1,0]
	v_pk_mul_f32 v[96:97], v[2:3], v[148:149] op_sel_hi:[1,0]
	v_pk_fma_f32 v[78:79], v[4:5], v[10:11], v[78:79] op_sel:[0,1,0] op_sel_hi:[1,1,1]
	v_pk_fma_f32 v[96:97], v[4:5], v[148:149], v[96:97] op_sel:[0,1,0] op_sel_hi:[1,1,1]
	v_pk_fma_f32 v[78:79], v[6:7], v[12:13], v[78:79] op_sel_hi:[1,0,1]
	v_pk_fma_f32 v[96:97], v[6:7], v[150:151], v[96:97] op_sel_hi:[1,0,1]
	v_pk_fma_f32 v[78:79], v[8:9], v[12:13], v[78:79] op_sel:[0,1,0] op_sel_hi:[1,1,1]
	v_pk_mul_f32 v[82:83], v[70:71], v[18:19] op_sel_hi:[1,0]
	v_pk_fma_f32 v[96:97], v[8:9], v[150:151], v[96:97] op_sel:[0,1,0] op_sel_hi:[1,1,1]
	v_pk_mul_f32 v[84:85], v[70:71], v[18:19] op_sel:[0,1] op_sel_hi:[1,1]
	v_add_f32_dpp v78, v78, v78 quad_perm:[1,0,3,2] row_mask:0xf bank_mask:0xf bound_ctrl:1
	v_add_f32_dpp v79, v79, v79 quad_perm:[1,0,3,2] row_mask:0xf bank_mask:0xf bound_ctrl:1
	v_pk_mul_f32 v[86:87], v[70:71], v[20:21] op_sel_hi:[1,0]
	ds_read_b128 v[132:135], v100 offset:17920
	v_add_f32_dpp v78, v78, v78 quad_perm:[2,3,0,1] row_mask:0xf bank_mask:0xf bound_ctrl:1
	v_add_f32_dpp v79, v79, v79 quad_perm:[2,3,0,1] row_mask:0xf bank_mask:0xf bound_ctrl:1
	v_pk_mul_f32 v[88:89], v[70:71], v[20:21] op_sel:[0,1] op_sel_hi:[1,1]
	ds_read_b128 v[140:143], v100 offset:18432
	v_add_f32_dpp v78, v78, v78 row_half_mirror row_mask:0xf bank_mask:0xf bound_ctrl:1
	v_add_f32_dpp v79, v79, v79 row_half_mirror row_mask:0xf bank_mask:0xf bound_ctrl:1
	v_pk_fma_f32 v[82:83], v[2:3], v[14:15], v[82:83] op_sel_hi:[1,0,1]
	ds_read_b128 v[136:139], v100 offset:18176
	v_add_f32_dpp v78, v78, v78 row_mirror row_mask:0xf bank_mask:0xf bound_ctrl:1
	v_add_f32_dpp v79, v79, v79 row_mirror row_mask:0xf bank_mask:0xf bound_ctrl:1
	v_pk_fma_f32 v[84:85], v[4:5], v[14:15], v[84:85] op_sel:[0,1,0] op_sel_hi:[1,1,1]
	ds_read_b128 v[144:147], v100 offset:18688
	v_pk_fma_f32 v[86:87], v[6:7], v[16:17], v[86:87] op_sel_hi:[1,0,1]
	ds_read_b128 v[148:151], v100 offset:18944
	v_pk_fma_f32 v[88:89], v[8:9], v[16:17], v[88:89] op_sel:[0,1,0] op_sel_hi:[1,1,1]
	ds_read_b128 v[74:77], v101 offset:112
	v_cndmask_b32_e64 v104, v90, v92, s[50:51]
	v_cndmask_b32_e64 v106, v92, v90, s[50:51]
	v_cndmask_b32_e64 v108, v94, v96, s[50:51]
	v_pk_fma_f32 v[2:3], v[78:79], v[22:23], v[82:83] op_sel_hi:[1,0,1]
	v_pk_fma_f32 v[4:5], v[78:79], v[22:23], v[84:85] op_sel:[0,1,0] op_sel_hi:[1,1,1]
	v_pk_fma_f32 v[6:7], v[78:79], v[24:25], v[86:87] op_sel_hi:[1,0,1]
	v_pk_fma_f32 v[8:9], v[78:79], v[24:25], v[88:89] op_sel:[0,1,0] op_sel_hi:[1,1,1]
	v_cndmask_b32_e64 v110, v96, v94, s[50:51]
	v_cndmask_b32_e64 v105, v91, v93, s[50:51]
	v_cndmask_b32_e64 v107, v93, v91, s[50:51]
	s_waitcnt lgkmcnt(6)
	v_pk_mul_f32 v[78:79], v[2:3], v[30:31] op_sel_hi:[1,0]
	v_pk_mul_f32 v[90:91], v[2:3], v[26:27] op_sel_hi:[1,0]
	v_pk_fma_f32 v[78:79], v[4:5], v[30:31], v[78:79] op_sel:[0,1,0] op_sel_hi:[1,1,1]
	v_pk_fma_f32 v[90:91], v[4:5], v[26:27], v[90:91] op_sel:[0,1,0] op_sel_hi:[1,1,1]
	v_pk_fma_f32 v[78:79], v[6:7], v[32:33], v[78:79] op_sel_hi:[1,0,1]
	v_pk_fma_f32 v[90:91], v[6:7], v[28:29], v[90:91] op_sel_hi:[1,0,1]
	v_pk_fma_f32 v[78:79], v[8:9], v[32:33], v[78:79] op_sel:[0,1,0] op_sel_hi:[1,1,1]
	v_pk_mul_f32 v[82:83], v[72:73], v[38:39] op_sel_hi:[1,0]
	v_pk_fma_f32 v[90:91], v[8:9], v[28:29], v[90:91] op_sel:[0,1,0] op_sel_hi:[1,1,1]
	v_pk_mul_f32 v[84:85], v[72:73], v[38:39] op_sel:[0,1] op_sel_hi:[1,1]
	v_add_f32_dpp v78, v78, v78 quad_perm:[1,0,3,2] row_mask:0xf bank_mask:0xf bound_ctrl:1
	v_add_f32_dpp v79, v79, v79 quad_perm:[1,0,3,2] row_mask:0xf bank_mask:0xf bound_ctrl:1
	v_pk_mul_f32 v[86:87], v[72:73], v[40:41] op_sel_hi:[1,0]
	ds_read_b128 v[10:13], v100 offset:19200
	v_add_f32_dpp v78, v78, v78 quad_perm:[2,3,0,1] row_mask:0xf bank_mask:0xf bound_ctrl:1
	v_add_f32_dpp v79, v79, v79 quad_perm:[2,3,0,1] row_mask:0xf bank_mask:0xf bound_ctrl:1
	v_pk_mul_f32 v[88:89], v[72:73], v[40:41] op_sel:[0,1] op_sel_hi:[1,1]
	ds_read_b128 v[18:21], v100 offset:19712
	v_add_f32_dpp v78, v78, v78 row_half_mirror row_mask:0xf bank_mask:0xf bound_ctrl:1
	v_add_f32_dpp v79, v79, v79 row_half_mirror row_mask:0xf bank_mask:0xf bound_ctrl:1
	v_pk_fma_f32 v[82:83], v[2:3], v[34:35], v[82:83] op_sel_hi:[1,0,1]
	ds_read_b128 v[14:17], v100 offset:19456
	v_add_f32_dpp v78, v78, v78 row_mirror row_mask:0xf bank_mask:0xf bound_ctrl:1
	v_add_f32_dpp v79, v79, v79 row_mirror row_mask:0xf bank_mask:0xf bound_ctrl:1
	v_pk_fma_f32 v[84:85], v[4:5], v[34:35], v[84:85] op_sel:[0,1,0] op_sel_hi:[1,1,1]
	ds_read_b128 v[22:25], v100 offset:19968
	v_pk_fma_f32 v[86:87], v[6:7], v[36:37], v[86:87] op_sel_hi:[1,0,1]
	ds_read_b128 v[26:29], v100 offset:20224
	v_pk_fma_f32 v[88:89], v[8:9], v[36:37], v[88:89] op_sel:[0,1,0] op_sel_hi:[1,1,1]
	v_cndmask_b32_e64 v109, v95, v97, s[50:51]
	v_cndmask_b32_e64 v111, v97, v95, s[50:51]
	v_add_f32_dpp v112, v106, v104 quad_perm:[1,0,3,2] row_mask:0xf bank_mask:0xf bound_ctrl:1
	v_pk_fma_f32 v[2:3], v[78:79], v[42:43], v[82:83] op_sel_hi:[1,0,1]
	v_pk_fma_f32 v[4:5], v[78:79], v[42:43], v[84:85] op_sel:[0,1,0] op_sel_hi:[1,1,1]
	v_pk_fma_f32 v[6:7], v[78:79], v[44:45], v[86:87] op_sel_hi:[1,0,1]
	v_pk_fma_f32 v[8:9], v[78:79], v[44:45], v[88:89] op_sel:[0,1,0] op_sel_hi:[1,1,1]
	v_add_f32_dpp v114, v110, v108 quad_perm:[1,0,3,2] row_mask:0xf bank_mask:0xf bound_ctrl:1
	v_add_f32_dpp v113, v107, v105 quad_perm:[1,0,3,2] row_mask:0xf bank_mask:0xf bound_ctrl:1
	v_add_f32_dpp v115, v111, v109 quad_perm:[1,0,3,2] row_mask:0xf bank_mask:0xf bound_ctrl:1
	s_waitcnt lgkmcnt(5)
; #define LAS __attribute__((address_space(3)))
; __device__ __forceinline__ void phase_scan(CParams& P, LAS unsigned char* lds) {
;     ...
;             f32x4 Ar0, Ar1, Aw0, Aw1, Ak0, Ak1, Aq0, Aq1, Ab0, Ab1, Br0, Br1, Bw0, Bw1, Bk0, Bk1, Bq0, Bq1, Bb0, Bb1; float Avv, Bvv;
; #pragma unroll 1
;             for (int c = 0; c < NCH; ++c) {
;                 __syncthreads();
;                 const LAS float* base = lf + (c & 1) * BUFF + 8 * oct;
;                 SC_LOAD(A, base);
; #pragma unroll 2
;                 for (int j = 0; j < CH; j += 2) { const LAS float* sp = base + j * STEPF;
;                     SC_LOAD(B, sp + STEPF); SC_STEP(A);
;                     SC_LOAD(A, sp + 2 * STEPF);
;                     SC_STEP(B); }
	v_pk_mul_f32 v[78:79], v[2:3], v[132:133] op_sel_hi:[1,0]
	v_pk_mul_f32 v[92:93], v[2:3], v[46:47] op_sel_hi:[1,0]
	v_pk_fma_f32 v[78:79], v[4:5], v[132:133], v[78:79] op_sel:[0,1,0] op_sel_hi:[1,1,1]
	v_pk_fma_f32 v[92:93], v[4:5], v[46:47], v[92:93] op_sel:[0,1,0] op_sel_hi:[1,1,1]
	v_pk_fma_f32 v[78:79], v[6:7], v[134:135], v[78:79] op_sel_hi:[1,0,1]
	v_pk_fma_f32 v[92:93], v[6:7], v[48:49], v[92:93] op_sel_hi:[1,0,1]
	v_pk_fma_f32 v[78:79], v[8:9], v[134:135], v[78:79] op_sel:[0,1,0] op_sel_hi:[1,1,1]
	v_pk_mul_f32 v[82:83], v[74:75], v[140:141] op_sel_hi:[1,0]
	v_pk_fma_f32 v[92:93], v[8:9], v[48:49], v[92:93] op_sel:[0,1,0] op_sel_hi:[1,1,1]
	v_pk_mul_f32 v[84:85], v[74:75], v[140:141] op_sel:[0,1] op_sel_hi:[1,1]
	v_add_f32_dpp v78, v78, v78 quad_perm:[1,0,3,2] row_mask:0xf bank_mask:0xf bound_ctrl:1
	v_add_f32_dpp v79, v79, v79 quad_perm:[1,0,3,2] row_mask:0xf bank_mask:0xf bound_ctrl:1
	v_pk_mul_f32 v[86:87], v[74:75], v[142:143] op_sel_hi:[1,0]
	ds_read_b128 v[30:33], v100 offset:20480
	v_add_f32_dpp v78, v78, v78 quad_perm:[2,3,0,1] row_mask:0xf bank_mask:0xf bound_ctrl:1
	v_add_f32_dpp v79, v79, v79 quad_perm:[2,3,0,1] row_mask:0xf bank_mask:0xf bound_ctrl:1
	v_pk_mul_f32 v[88:89], v[74:75], v[142:143] op_sel:[0,1] op_sel_hi:[1,1]
	ds_read_b128 v[38:41], v100 offset:20992
	v_add_f32_dpp v78, v78, v78 row_half_mirror row_mask:0xf bank_mask:0xf bound_ctrl:1
	v_add_f32_dpp v79, v79, v79 row_half_mirror row_mask:0xf bank_mask:0xf bound_ctrl:1
	v_pk_fma_f32 v[82:83], v[2:3], v[136:137], v[82:83] op_sel_hi:[1,0,1]
	ds_read_b128 v[34:37], v100 offset:20736
	v_add_f32_dpp v78, v78, v78 row_mirror row_mask:0xf bank_mask:0xf bound_ctrl:1
	v_add_f32_dpp v79, v79, v79 row_mirror row_mask:0xf bank_mask:0xf bound_ctrl:1
	v_pk_fma_f32 v[84:85], v[4:5], v[136:137], v[84:85] op_sel:[0,1,0] op_sel_hi:[1,1,1]
	ds_read_b128 v[42:45], v100 offset:21248
	v_pk_fma_f32 v[86:87], v[6:7], v[138:139], v[86:87] op_sel_hi:[1,0,1]
	ds_read_b128 v[46:49], v100 offset:21504
	v_pk_fma_f32 v[88:89], v[8:9], v[138:139], v[88:89] op_sel:[0,1,0] op_sel_hi:[1,1,1]
	ds_read_b128 v[70:73], v101 offset:128
	v_cndmask_b32_e64 v116, v112, v114, s[52:53]
	v_cndmask_b32_e64 v118, v114, v112, s[52:53]
	v_cndmask_b32_e64 v117, v113, v115, s[52:53]
	v_pk_fma_f32 v[2:3], v[78:79], v[144:145], v[82:83] op_sel_hi:[1,0,1]
	v_pk_fma_f32 v[4:5], v[78:79], v[144:145], v[84:85] op_sel:[0,1,0] op_sel_hi:[1,1,1]
	v_pk_fma_f32 v[6:7], v[78:79], v[146:147], v[86:87] op_sel_hi:[1,0,1]
	v_pk_fma_f32 v[8:9], v[78:79], v[146:147], v[88:89] op_sel:[0,1,0] op_sel_hi:[1,1,1]
	v_cndmask_b32_e64 v119, v115, v113, s[52:53]
	v_add_f32_dpp v120, v118, v116 quad_perm:[2,3,0,1] row_mask:0xf bank_mask:0xf bound_ctrl:1
	s_nop 0
	v_add_f32_dpp v121, v119, v117 quad_perm:[2,3,0,1] row_mask:0xf bank_mask:0xf bound_ctrl:1
	s_waitcnt lgkmcnt(6)
	v_pk_mul_f32 v[78:79], v[2:3], v[10:11] op_sel_hi:[1,0]
	v_pk_mul_f32 v[94:95], v[2:3], v[148:149] op_sel_hi:[1,0]
	v_pk_fma_f32 v[78:79], v[4:5], v[10:11], v[78:79] op_sel:[0,1,0] op_sel_hi:[1,1,1]
	v_pk_fma_f32 v[94:95], v[4:5], v[148:149], v[94:95] op_sel:[0,1,0] op_sel_hi:[1,1,1]
	v_pk_fma_f32 v[78:79], v[6:7], v[12:13], v[78:79] op_sel_hi:[1,0,1]
	v_pk_fma_f32 v[94:95], v[6:7], v[150:151], v[94:95] op_sel_hi:[1,0,1]
	v_pk_fma_f32 v[78:79], v[8:9], v[12:13], v[78:79] op_sel:[0,1,0] op_sel_hi:[1,1,1]
	v_pk_mul_f32 v[82:83], v[76:77], v[18:19] op_sel_hi:[1,0]
	v_pk_fma_f32 v[94:95], v[8:9], v[150:151], v[94:95] op_sel:[0,1,0] op_sel_hi:[1,1,1]
	v_pk_mul_f32 v[84:85], v[76:77], v[18:19] op_sel:[0,1] op_sel_hi:[1,1]
	v_add_f32_dpp v78, v78, v78 quad_perm:[1,0,3,2] row_mask:0xf bank_mask:0xf bound_ctrl:1
	v_add_f32_dpp v79, v79, v79 quad_perm:[1,0,3,2] row_mask:0xf bank_mask:0xf bound_ctrl:1
	v_pk_mul_f32 v[86:87], v[76:77], v[20:21] op_sel_hi:[1,0]
	ds_read_b128 v[132:135], v100 offset:21760
	v_add_f32_dpp v78, v78, v78 quad_perm:[2,3,0,1] row_mask:0xf bank_mask:0xf bound_ctrl:1
	v_add_f32_dpp v79, v79, v79 quad_perm:[2,3,0,1] row_mask:0xf bank_mask:0xf bound_ctrl:1
	v_pk_mul_f32 v[88:89], v[76:77], v[20:21] op_sel:[0,1] op_sel_hi:[1,1]
	ds_read_b128 v[140:143], v100 offset:22272
	v_add_f32_dpp v78, v78, v78 row_half_mirror row_mask:0xf bank_mask:0xf bound_ctrl:1
	v_add_f32_dpp v79, v79, v79 row_half_mirror row_mask:0xf bank_mask:0xf bound_ctrl:1
	v_pk_fma_f32 v[82:83], v[2:3], v[14:15], v[82:83] op_sel_hi:[1,0,1]
	ds_read_b128 v[136:139], v100 offset:22016
	v_add_f32_dpp v78, v78, v78 row_mirror row_mask:0xf bank_mask:0xf bound_ctrl:1
	v_add_f32_dpp v79, v79, v79 row_mirror row_mask:0xf bank_mask:0xf bound_ctrl:1
	v_pk_fma_f32 v[84:85], v[4:5], v[14:15], v[84:85] op_sel:[0,1,0] op_sel_hi:[1,1,1]
	ds_read_b128 v[144:147], v100 offset:22528
	v_pk_fma_f32 v[86:87], v[6:7], v[16:17], v[86:87] op_sel_hi:[1,0,1]
	ds_read_b128 v[148:151], v100 offset:22784
	v_pk_fma_f32 v[88:89], v[8:9], v[16:17], v[88:89] op_sel:[0,1,0] op_sel_hi:[1,1,1]
	v_add_f32_dpp v120, v120, v120 row_ror:4 row_mask:0xf bank_mask:0xf bound_ctrl:1
	v_add_f32_dpp v121, v121, v121 row_ror:4 row_mask:0xf bank_mask:0xf bound_ctrl:1
	s_nop 0
	v_add_f32_dpp v120, v120, v120 row_ror:8 row_mask:0xf bank_mask:0xf bound_ctrl:1
	v_pk_fma_f32 v[2:3], v[78:79], v[22:23], v[82:83] op_sel_hi:[1,0,1]
	v_pk_fma_f32 v[4:5], v[78:79], v[22:23], v[84:85] op_sel:[0,1,0] op_sel_hi:[1,1,1]
	v_pk_fma_f32 v[6:7], v[78:79], v[24:25], v[86:87] op_sel_hi:[1,0,1]
	v_pk_fma_f32 v[8:9], v[78:79], v[24:25], v[88:89] op_sel:[0,1,0] op_sel_hi:[1,1,1]
	v_add_f32_dpp v121, v121, v121 row_ror:8 row_mask:0xf bank_mask:0xf bound_ctrl:1
	global_store_dwordx2 v102, v[120:121], s[10:11]
	v_add_u32_e32 v102, s13, v102
	s_waitcnt lgkmcnt(5)
; #define LAS __attribute__((address_space(3)))
; __device__ __forceinline__ void phase_scan(CParams& P, LAS unsigned char* lds) {
;     ...
;             f32x4 Ar0, Ar1, Aw0, Aw1, Ak0, Ak1, Aq0, Aq1, Ab0, Ab1, Br0, Br1, Bw0, Bw1, Bk0, Bk1, Bq0, Bq1, Bb0, Bb1; float Avv, Bvv;
; #pragma unroll 1
;             for (int c = 0; c < NCH; ++c) {
;                 __syncthreads();
;                 const LAS float* base = lf + (c & 1) * BUFF + 8 * oct;
;                 SC_LOAD(A, base);
; #pragma unroll 2
;                 for (int j = 0; j < CH; j += 2) { const LAS float* sp = base + j * STEPF;
;                     SC_LOAD(B, sp + STEPF); SC_STEP(A);
;                     SC_LOAD(A, sp + 2 * STEPF);
;                     SC_STEP(B); }
	v_pk_mul_f32 v[78:79], v[2:3], v[30:31] op_sel_hi:[1,0]
	v_pk_mul_f32 v[96:97], v[2:3], v[26:27] op_sel_hi:[1,0]
	v_pk_fma_f32 v[78:79], v[4:5], v[30:31], v[78:79] op_sel:[0,1,0] op_sel_hi:[1,1,1]
	v_pk_fma_f32 v[96:97], v[4:5], v[26:27], v[96:97] op_sel:[0,1,0] op_sel_hi:[1,1,1]
	v_pk_fma_f32 v[78:79], v[6:7], v[32:33], v[78:79] op_sel_hi:[1,0,1]
	v_pk_fma_f32 v[96:97], v[6:7], v[28:29], v[96:97] op_sel_hi:[1,0,1]
	v_pk_fma_f32 v[78:79], v[8:9], v[32:33], v[78:79] op_sel:[0,1,0] op_sel_hi:[1,1,1]
	v_pk_mul_f32 v[82:83], v[70:71], v[38:39] op_sel_hi:[1,0]
	v_pk_fma_f32 v[96:97], v[8:9], v[28:29], v[96:97] op_sel:[0,1,0] op_sel_hi:[1,1,1]
	v_pk_mul_f32 v[84:85], v[70:71], v[38:39] op_sel:[0,1] op_sel_hi:[1,1]
	v_add_f32_dpp v78, v78, v78 quad_perm:[1,0,3,2] row_mask:0xf bank_mask:0xf bound_ctrl:1
	v_add_f32_dpp v79, v79, v79 quad_perm:[1,0,3,2] row_mask:0xf bank_mask:0xf bound_ctrl:1
	v_pk_mul_f32 v[86:87], v[70:71], v[40:41] op_sel_hi:[1,0]
	ds_read_b128 v[10:13], v100 offset:23040
	v_add_f32_dpp v78, v78, v78 quad_perm:[2,3,0,1] row_mask:0xf bank_mask:0xf bound_ctrl:1
	v_add_f32_dpp v79, v79, v79 quad_perm:[2,3,0,1] row_mask:0xf bank_mask:0xf bound_ctrl:1
	v_pk_mul_f32 v[88:89], v[70:71], v[40:41] op_sel:[0,1] op_sel_hi:[1,1]
	ds_read_b128 v[18:21], v100 offset:23552
	v_add_f32_dpp v78, v78, v78 row_half_mirror row_mask:0xf bank_mask:0xf bound_ctrl:1
	v_add_f32_dpp v79, v79, v79 row_half_mirror row_mask:0xf bank_mask:0xf bound_ctrl:1
	v_pk_fma_f32 v[82:83], v[2:3], v[34:35], v[82:83] op_sel_hi:[1,0,1]
	ds_read_b128 v[14:17], v100 offset:23296
	v_add_f32_dpp v78, v78, v78 row_mirror row_mask:0xf bank_mask:0xf bound_ctrl:1
	v_add_f32_dpp v79, v79, v79 row_mirror row_mask:0xf bank_mask:0xf bound_ctrl:1
	v_pk_fma_f32 v[84:85], v[4:5], v[34:35], v[84:85] op_sel:[0,1,0] op_sel_hi:[1,1,1]
	ds_read_b128 v[22:25], v100 offset:23808
	v_pk_fma_f32 v[86:87], v[6:7], v[36:37], v[86:87] op_sel_hi:[1,0,1]
	ds_read_b128 v[26:29], v100 offset:24064
	v_pk_fma_f32 v[88:89], v[8:9], v[36:37], v[88:89] op_sel:[0,1,0] op_sel_hi:[1,1,1]
	ds_read_b128 v[74:77], v101 offset:144
	v_cndmask_b32_e64 v104, v90, v92, s[50:51]
	v_cndmask_b32_e64 v106, v92, v90, s[50:51]
	v_cndmask_b32_e64 v108, v94, v96, s[50:51]
	v_pk_fma_f32 v[2:3], v[78:79], v[42:43], v[82:83] op_sel_hi:[1,0,1]
	v_pk_fma_f32 v[4:5], v[78:79], v[42:43], v[84:85] op_sel:[0,1,0] op_sel_hi:[1,1,1]
	v_pk_fma_f32 v[6:7], v[78:79], v[44:45], v[86:87] op_sel_hi:[1,0,1]
	v_pk_fma_f32 v[8:9], v[78:79], v[44:45], v[88:89] op_sel:[0,1,0] op_sel_hi:[1,1,1]
	v_cndmask_b32_e64 v110, v96, v94, s[50:51]
	v_cndmask_b32_e64 v105, v91, v93, s[50:51]
	v_cndmask_b32_e64 v107, v93, v91, s[50:51]
	s_waitcnt lgkmcnt(6)
	v_pk_mul_f32 v[78:79], v[2:3], v[132:133] op_sel_hi:[1,0]
	v_pk_mul_f32 v[90:91], v[2:3], v[46:47] op_sel_hi:[1,0]
	v_pk_fma_f32 v[78:79], v[4:5], v[132:133], v[78:79] op_sel:[0,1,0] op_sel_hi:[1,1,1]
	v_pk_fma_f32 v[90:91], v[4:5], v[46:47], v[90:91] op_sel:[0,1,0] op_sel_hi:[1,1,1]
	v_pk_fma_f32 v[78:79], v[6:7], v[134:135], v[78:79] op_sel_hi:[1,0,1]
	v_pk_fma_f32 v[90:91], v[6:7], v[48:49], v[90:91] op_sel_hi:[1,0,1]
	v_pk_fma_f32 v[78:79], v[8:9], v[134:135], v[78:79] op_sel:[0,1,0] op_sel_hi:[1,1,1]
	v_pk_mul_f32 v[82:83], v[72:73], v[140:141] op_sel_hi:[1,0]
	v_pk_fma_f32 v[90:91], v[8:9], v[48:49], v[90:91] op_sel:[0,1,0] op_sel_hi:[1,1,1]
	v_pk_mul_f32 v[84:85], v[72:73], v[140:141] op_sel:[0,1] op_sel_hi:[1,1]
	v_add_f32_dpp v78, v78, v78 quad_perm:[1,0,3,2] row_mask:0xf bank_mask:0xf bound_ctrl:1
	v_add_f32_dpp v79, v79, v79 quad_perm:[1,0,3,2] row_mask:0xf bank_mask:0xf bound_ctrl:1
	v_pk_mul_f32 v[86:87], v[72:73], v[142:143] op_sel_hi:[1,0]
	ds_read_b128 v[30:33], v100 offset:24320
	v_add_f32_dpp v78, v78, v78 quad_perm:[2,3,0,1] row_mask:0xf bank_mask:0xf bound_ctrl:1
	v_add_f32_dpp v79, v79, v79 quad_perm:[2,3,0,1] row_mask:0xf bank_mask:0xf bound_ctrl:1
	v_pk_mul_f32 v[88:89], v[72:73], v[142:143] op_sel:[0,1] op_sel_hi:[1,1]
	ds_read_b128 v[38:41], v100 offset:24832
	v_add_f32_dpp v78, v78, v78 row_half_mirror row_mask:0xf bank_mask:0xf bound_ctrl:1
	v_add_f32_dpp v79, v79, v79 row_half_mirror row_mask:0xf bank_mask:0xf bound_ctrl:1
	v_pk_fma_f32 v[82:83], v[2:3], v[136:137], v[82:83] op_sel_hi:[1,0,1]
	ds_read_b128 v[34:37], v100 offset:24576
	v_add_f32_dpp v78, v78, v78 row_mirror row_mask:0xf bank_mask:0xf bound_ctrl:1
	v_add_f32_dpp v79, v79, v79 row_mirror row_mask:0xf bank_mask:0xf bound_ctrl:1
	v_pk_fma_f32 v[84:85], v[4:5], v[136:137], v[84:85] op_sel:[0,1,0] op_sel_hi:[1,1,1]
	ds_read_b128 v[42:45], v100 offset:25088
	v_pk_fma_f32 v[86:87], v[6:7], v[138:139], v[86:87] op_sel_hi:[1,0,1]
	ds_read_b128 v[46:49], v100 offset:25344
	v_pk_fma_f32 v[88:89], v[8:9], v[138:139], v[88:89] op_sel:[0,1,0] op_sel_hi:[1,1,1]
	v_cndmask_b32_e64 v109, v95, v97, s[50:51]
	v_cndmask_b32_e64 v111, v97, v95, s[50:51]
	v_add_f32_dpp v112, v106, v104 quad_perm:[1,0,3,2] row_mask:0xf bank_mask:0xf bound_ctrl:1
	v_pk_fma_f32 v[2:3], v[78:79], v[144:145], v[82:83] op_sel_hi:[1,0,1]
	v_pk_fma_f32 v[4:5], v[78:79], v[144:145], v[84:85] op_sel:[0,1,0] op_sel_hi:[1,1,1]
	v_pk_fma_f32 v[6:7], v[78:79], v[146:147], v[86:87] op_sel_hi:[1,0,1]
	v_pk_fma_f32 v[8:9], v[78:79], v[146:147], v[88:89] op_sel:[0,1,0] op_sel_hi:[1,1,1]
	v_add_f32_dpp v114, v110, v108 quad_perm:[1,0,3,2] row_mask:0xf bank_mask:0xf bound_ctrl:1
	v_add_f32_dpp v113, v107, v105 quad_perm:[1,0,3,2] row_mask:0xf bank_mask:0xf bound_ctrl:1
	v_add_f32_dpp v115, v111, v109 quad_perm:[1,0,3,2] row_mask:0xf bank_mask:0xf bound_ctrl:1
	s_waitcnt lgkmcnt(5)
; #define LAS __attribute__((address_space(3)))
; __device__ __forceinline__ void phase_scan(CParams& P, LAS unsigned char* lds) {
;     ...
;             f32x4 Ar0, Ar1, Aw0, Aw1, Ak0, Ak1, Aq0, Aq1, Ab0, Ab1, Br0, Br1, Bw0, Bw1, Bk0, Bk1, Bq0, Bq1, Bb0, Bb1; float Avv, Bvv;
; #pragma unroll 1
;             for (int c = 0; c < NCH; ++c) {
;                 __syncthreads();
;                 const LAS float* base = lf + (c & 1) * BUFF + 8 * oct;
;                 SC_LOAD(A, base);
; #pragma unroll 2
;                 for (int j = 0; j < CH; j += 2) { const LAS float* sp = base + j * STEPF;
;                     SC_LOAD(B, sp + STEPF); SC_STEP(A);
;                     SC_LOAD(A, sp + 2 * STEPF);
;                     SC_STEP(B); }
	v_pk_mul_f32 v[78:79], v[2:3], v[10:11] op_sel_hi:[1,0]
	v_pk_mul_f32 v[92:93], v[2:3], v[148:149] op_sel_hi:[1,0]
	v_pk_fma_f32 v[78:79], v[4:5], v[10:11], v[78:79] op_sel:[0,1,0] op_sel_hi:[1,1,1]
	v_pk_fma_f32 v[92:93], v[4:5], v[148:149], v[92:93] op_sel:[0,1,0] op_sel_hi:[1,1,1]
	v_pk_fma_f32 v[78:79], v[6:7], v[12:13], v[78:79] op_sel_hi:[1,0,1]
	v_pk_fma_f32 v[92:93], v[6:7], v[150:151], v[92:93] op_sel_hi:[1,0,1]
	v_pk_fma_f32 v[78:79], v[8:9], v[12:13], v[78:79] op_sel:[0,1,0] op_sel_hi:[1,1,1]
	v_pk_mul_f32 v[82:83], v[74:75], v[18:19] op_sel_hi:[1,0]
	v_pk_fma_f32 v[92:93], v[8:9], v[150:151], v[92:93] op_sel:[0,1,0] op_sel_hi:[1,1,1]
	v_pk_mul_f32 v[84:85], v[74:75], v[18:19] op_sel:[0,1] op_sel_hi:[1,1]
	v_add_f32_dpp v78, v78, v78 quad_perm:[1,0,3,2] row_mask:0xf bank_mask:0xf bound_ctrl:1
	v_add_f32_dpp v79, v79, v79 quad_perm:[1,0,3,2] row_mask:0xf bank_mask:0xf bound_ctrl:1
	v_pk_mul_f32 v[86:87], v[74:75], v[20:21] op_sel_hi:[1,0]
	ds_read_b128 v[132:135], v100 offset:25600
	v_add_f32_dpp v78, v78, v78 quad_perm:[2,3,0,1] row_mask:0xf bank_mask:0xf bound_ctrl:1
	v_add_f32_dpp v79, v79, v79 quad_perm:[2,3,0,1] row_mask:0xf bank_mask:0xf bound_ctrl:1
	v_pk_mul_f32 v[88:89], v[74:75], v[20:21] op_sel:[0,1] op_sel_hi:[1,1]
	ds_read_b128 v[140:143], v100 offset:26112
	v_add_f32_dpp v78, v78, v78 row_half_mirror row_mask:0xf bank_mask:0xf bound_ctrl:1
	v_add_f32_dpp v79, v79, v79 row_half_mirror row_mask:0xf bank_mask:0xf bound_ctrl:1
	v_pk_fma_f32 v[82:83], v[2:3], v[14:15], v[82:83] op_sel_hi:[1,0,1]
	ds_read_b128 v[136:139], v100 offset:25856
	v_add_f32_dpp v78, v78, v78 row_mirror row_mask:0xf bank_mask:0xf bound_ctrl:1
	v_add_f32_dpp v79, v79, v79 row_mirror row_mask:0xf bank_mask:0xf bound_ctrl:1
	v_pk_fma_f32 v[84:85], v[4:5], v[14:15], v[84:85] op_sel:[0,1,0] op_sel_hi:[1,1,1]
	ds_read_b128 v[144:147], v100 offset:26368
	v_pk_fma_f32 v[86:87], v[6:7], v[16:17], v[86:87] op_sel_hi:[1,0,1]
	ds_read_b128 v[148:151], v100 offset:26624
	v_pk_fma_f32 v[88:89], v[8:9], v[16:17], v[88:89] op_sel:[0,1,0] op_sel_hi:[1,1,1]
	ds_read_b128 v[70:73], v101 offset:160
	v_cndmask_b32_e64 v116, v112, v114, s[52:53]
	v_cndmask_b32_e64 v118, v114, v112, s[52:53]
	v_cndmask_b32_e64 v117, v113, v115, s[52:53]
	v_pk_fma_f32 v[2:3], v[78:79], v[22:23], v[82:83] op_sel_hi:[1,0,1]
	v_pk_fma_f32 v[4:5], v[78:79], v[22:23], v[84:85] op_sel:[0,1,0] op_sel_hi:[1,1,1]
	v_pk_fma_f32 v[6:7], v[78:79], v[24:25], v[86:87] op_sel_hi:[1,0,1]
	v_pk_fma_f32 v[8:9], v[78:79], v[24:25], v[88:89] op_sel:[0,1,0] op_sel_hi:[1,1,1]
	v_cndmask_b32_e64 v119, v115, v113, s[52:53]
	v_add_f32_dpp v120, v118, v116 quad_perm:[2,3,0,1] row_mask:0xf bank_mask:0xf bound_ctrl:1
	s_nop 0
	v_add_f32_dpp v121, v119, v117 quad_perm:[2,3,0,1] row_mask:0xf bank_mask:0xf bound_ctrl:1
	s_waitcnt lgkmcnt(6)
	v_pk_mul_f32 v[78:79], v[2:3], v[30:31] op_sel_hi:[1,0]
	v_pk_mul_f32 v[94:95], v[2:3], v[26:27] op_sel_hi:[1,0]
	v_pk_fma_f32 v[78:79], v[4:5], v[30:31], v[78:79] op_sel:[0,1,0] op_sel_hi:[1,1,1]
	v_pk_fma_f32 v[94:95], v[4:5], v[26:27], v[94:95] op_sel:[0,1,0] op_sel_hi:[1,1,1]
	v_pk_fma_f32 v[78:79], v[6:7], v[32:33], v[78:79] op_sel_hi:[1,0,1]
	v_pk_fma_f32 v[94:95], v[6:7], v[28:29], v[94:95] op_sel_hi:[1,0,1]
	v_pk_fma_f32 v[78:79], v[8:9], v[32:33], v[78:79] op_sel:[0,1,0] op_sel_hi:[1,1,1]
	v_pk_mul_f32 v[82:83], v[76:77], v[38:39] op_sel_hi:[1,0]
	v_pk_fma_f32 v[94:95], v[8:9], v[28:29], v[94:95] op_sel:[0,1,0] op_sel_hi:[1,1,1]
	v_pk_mul_f32 v[84:85], v[76:77], v[38:39] op_sel:[0,1] op_sel_hi:[1,1]
	v_add_f32_dpp v78, v78, v78 quad_perm:[1,0,3,2] row_mask:0xf bank_mask:0xf bound_ctrl:1
	v_add_f32_dpp v79, v79, v79 quad_perm:[1,0,3,2] row_mask:0xf bank_mask:0xf bound_ctrl:1
	v_pk_mul_f32 v[86:87], v[76:77], v[40:41] op_sel_hi:[1,0]
	ds_read_b128 v[10:13], v100 offset:26880
	v_add_f32_dpp v78, v78, v78 quad_perm:[2,3,0,1] row_mask:0xf bank_mask:0xf bound_ctrl:1
	v_add_f32_dpp v79, v79, v79 quad_perm:[2,3,0,1] row_mask:0xf bank_mask:0xf bound_ctrl:1
	v_pk_mul_f32 v[88:89], v[76:77], v[40:41] op_sel:[0,1] op_sel_hi:[1,1]
	ds_read_b128 v[18:21], v100 offset:27392
	v_add_f32_dpp v78, v78, v78 row_half_mirror row_mask:0xf bank_mask:0xf bound_ctrl:1
	v_add_f32_dpp v79, v79, v79 row_half_mirror row_mask:0xf bank_mask:0xf bound_ctrl:1
	v_pk_fma_f32 v[82:83], v[2:3], v[34:35], v[82:83] op_sel_hi:[1,0,1]
	ds_read_b128 v[14:17], v100 offset:27136
	v_add_f32_dpp v78, v78, v78 row_mirror row_mask:0xf bank_mask:0xf bound_ctrl:1
	v_add_f32_dpp v79, v79, v79 row_mirror row_mask:0xf bank_mask:0xf bound_ctrl:1
	v_pk_fma_f32 v[84:85], v[4:5], v[34:35], v[84:85] op_sel:[0,1,0] op_sel_hi:[1,1,1]
	ds_read_b128 v[22:25], v100 offset:27648
	v_pk_fma_f32 v[86:87], v[6:7], v[36:37], v[86:87] op_sel_hi:[1,0,1]
	ds_read_b128 v[26:29], v100 offset:27904
	v_pk_fma_f32 v[88:89], v[8:9], v[36:37], v[88:89] op_sel:[0,1,0] op_sel_hi:[1,1,1]
	v_add_f32_dpp v120, v120, v120 row_ror:4 row_mask:0xf bank_mask:0xf bound_ctrl:1
	v_add_f32_dpp v121, v121, v121 row_ror:4 row_mask:0xf bank_mask:0xf bound_ctrl:1
	s_nop 0
	v_add_f32_dpp v120, v120, v120 row_ror:8 row_mask:0xf bank_mask:0xf bound_ctrl:1
	v_pk_fma_f32 v[2:3], v[78:79], v[42:43], v[82:83] op_sel_hi:[1,0,1]
	v_pk_fma_f32 v[4:5], v[78:79], v[42:43], v[84:85] op_sel:[0,1,0] op_sel_hi:[1,1,1]
	v_pk_fma_f32 v[6:7], v[78:79], v[44:45], v[86:87] op_sel_hi:[1,0,1]
	v_pk_fma_f32 v[8:9], v[78:79], v[44:45], v[88:89] op_sel:[0,1,0] op_sel_hi:[1,1,1]
	v_add_f32_dpp v121, v121, v121 row_ror:8 row_mask:0xf bank_mask:0xf bound_ctrl:1
	global_store_dwordx2 v102, v[120:121], s[10:11]
	v_add_u32_e32 v102, s13, v102
	s_waitcnt lgkmcnt(5)
; #define LAS __attribute__((address_space(3)))
; __device__ __forceinline__ void phase_scan(CParams& P, LAS unsigned char* lds) {
;     ...
;             f32x4 Ar0, Ar1, Aw0, Aw1, Ak0, Ak1, Aq0, Aq1, Ab0, Ab1, Br0, Br1, Bw0, Bw1, Bk0, Bk1, Bq0, Bq1, Bb0, Bb1; float Avv, Bvv;
; #pragma unroll 1
;             for (int c = 0; c < NCH; ++c) {
;                 __syncthreads();
;                 const LAS float* base = lf + (c & 1) * BUFF + 8 * oct;
;                 SC_LOAD(A, base);
; #pragma unroll 2
;                 for (int j = 0; j < CH; j += 2) { const LAS float* sp = base + j * STEPF;
;                     SC_LOAD(B, sp + STEPF); SC_STEP(A);
;                     SC_LOAD(A, sp + 2 * STEPF);
;                     SC_STEP(B); }
	v_pk_mul_f32 v[78:79], v[2:3], v[132:133] op_sel_hi:[1,0]
	v_pk_mul_f32 v[96:97], v[2:3], v[46:47] op_sel_hi:[1,0]
	v_pk_fma_f32 v[78:79], v[4:5], v[132:133], v[78:79] op_sel:[0,1,0] op_sel_hi:[1,1,1]
	v_pk_fma_f32 v[96:97], v[4:5], v[46:47], v[96:97] op_sel:[0,1,0] op_sel_hi:[1,1,1]
	v_pk_fma_f32 v[78:79], v[6:7], v[134:135], v[78:79] op_sel_hi:[1,0,1]
	v_pk_fma_f32 v[96:97], v[6:7], v[48:49], v[96:97] op_sel_hi:[1,0,1]
	v_pk_fma_f32 v[78:79], v[8:9], v[134:135], v[78:79] op_sel:[0,1,0] op_sel_hi:[1,1,1]
	v_pk_mul_f32 v[82:83], v[70:71], v[140:141] op_sel_hi:[1,0]
	v_pk_fma_f32 v[96:97], v[8:9], v[48:49], v[96:97] op_sel:[0,1,0] op_sel_hi:[1,1,1]
	v_pk_mul_f32 v[84:85], v[70:71], v[140:141] op_sel:[0,1] op_sel_hi:[1,1]
	v_add_f32_dpp v78, v78, v78 quad_perm:[1,0,3,2] row_mask:0xf bank_mask:0xf bound_ctrl:1
	v_add_f32_dpp v79, v79, v79 quad_perm:[1,0,3,2] row_mask:0xf bank_mask:0xf bound_ctrl:1
	v_pk_mul_f32 v[86:87], v[70:71], v[142:143] op_sel_hi:[1,0]
	ds_read_b128 v[30:33], v100 offset:28160
	v_add_f32_dpp v78, v78, v78 quad_perm:[2,3,0,1] row_mask:0xf bank_mask:0xf bound_ctrl:1
	v_add_f32_dpp v79, v79, v79 quad_perm:[2,3,0,1] row_mask:0xf bank_mask:0xf bound_ctrl:1
	v_pk_mul_f32 v[88:89], v[70:71], v[142:143] op_sel:[0,1] op_sel_hi:[1,1]
	ds_read_b128 v[38:41], v100 offset:28672
	v_add_f32_dpp v78, v78, v78 row_half_mirror row_mask:0xf bank_mask:0xf bound_ctrl:1
	v_add_f32_dpp v79, v79, v79 row_half_mirror row_mask:0xf bank_mask:0xf bound_ctrl:1
	v_pk_fma_f32 v[82:83], v[2:3], v[136:137], v[82:83] op_sel_hi:[1,0,1]
	ds_read_b128 v[34:37], v100 offset:28416
	v_add_f32_dpp v78, v78, v78 row_mirror row_mask:0xf bank_mask:0xf bound_ctrl:1
	v_add_f32_dpp v79, v79, v79 row_mirror row_mask:0xf bank_mask:0xf bound_ctrl:1
	v_pk_fma_f32 v[84:85], v[4:5], v[136:137], v[84:85] op_sel:[0,1,0] op_sel_hi:[1,1,1]
	ds_read_b128 v[42:45], v100 offset:28928
	v_pk_fma_f32 v[86:87], v[6:7], v[138:139], v[86:87] op_sel_hi:[1,0,1]
	ds_read_b128 v[46:49], v100 offset:29184
	v_pk_fma_f32 v[88:89], v[8:9], v[138:139], v[88:89] op_sel:[0,1,0] op_sel_hi:[1,1,1]
	ds_read_b128 v[74:77], v101 offset:176
	v_cndmask_b32_e64 v104, v90, v92, s[50:51]
	v_cndmask_b32_e64 v106, v92, v90, s[50:51]
	v_cndmask_b32_e64 v108, v94, v96, s[50:51]
	v_pk_fma_f32 v[2:3], v[78:79], v[144:145], v[82:83] op_sel_hi:[1,0,1]
	v_pk_fma_f32 v[4:5], v[78:79], v[144:145], v[84:85] op_sel:[0,1,0] op_sel_hi:[1,1,1]
	v_pk_fma_f32 v[6:7], v[78:79], v[146:147], v[86:87] op_sel_hi:[1,0,1]
	v_pk_fma_f32 v[8:9], v[78:79], v[146:147], v[88:89] op_sel:[0,1,0] op_sel_hi:[1,1,1]
	v_cndmask_b32_e64 v110, v96, v94, s[50:51]
	v_cndmask_b32_e64 v105, v91, v93, s[50:51]
	v_cndmask_b32_e64 v107, v93, v91, s[50:51]
	s_waitcnt lgkmcnt(6)
	v_pk_mul_f32 v[78:79], v[2:3], v[10:11] op_sel_hi:[1,0]
	v_pk_mul_f32 v[90:91], v[2:3], v[148:149] op_sel_hi:[1,0]
	v_pk_fma_f32 v[78:79], v[4:5], v[10:11], v[78:79] op_sel:[0,1,0] op_sel_hi:[1,1,1]
	v_pk_fma_f32 v[90:91], v[4:5], v[148:149], v[90:91] op_sel:[0,1,0] op_sel_hi:[1,1,1]
	v_pk_fma_f32 v[78:79], v[6:7], v[12:13], v[78:79] op_sel_hi:[1,0,1]
	v_pk_fma_f32 v[90:91], v[6:7], v[150:151], v[90:91] op_sel_hi:[1,0,1]
	v_pk_fma_f32 v[78:79], v[8:9], v[12:13], v[78:79] op_sel:[0,1,0] op_sel_hi:[1,1,1]
	v_pk_mul_f32 v[82:83], v[72:73], v[18:19] op_sel_hi:[1,0]
	v_pk_fma_f32 v[90:91], v[8:9], v[150:151], v[90:91] op_sel:[0,1,0] op_sel_hi:[1,1,1]
	v_pk_mul_f32 v[84:85], v[72:73], v[18:19] op_sel:[0,1] op_sel_hi:[1,1]
	v_add_f32_dpp v78, v78, v78 quad_perm:[1,0,3,2] row_mask:0xf bank_mask:0xf bound_ctrl:1
	v_add_f32_dpp v79, v79, v79 quad_perm:[1,0,3,2] row_mask:0xf bank_mask:0xf bound_ctrl:1
	v_pk_mul_f32 v[86:87], v[72:73], v[20:21] op_sel_hi:[1,0]
	ds_read_b128 v[132:135], v100 offset:29440
	v_add_f32_dpp v78, v78, v78 quad_perm:[2,3,0,1] row_mask:0xf bank_mask:0xf bound_ctrl:1
	v_add_f32_dpp v79, v79, v79 quad_perm:[2,3,0,1] row_mask:0xf bank_mask:0xf bound_ctrl:1
	v_pk_mul_f32 v[88:89], v[72:73], v[20:21] op_sel:[0,1] op_sel_hi:[1,1]
	ds_read_b128 v[140:143], v100 offset:29952
	v_add_f32_dpp v78, v78, v78 row_half_mirror row_mask:0xf bank_mask:0xf bound_ctrl:1
	v_add_f32_dpp v79, v79, v79 row_half_mirror row_mask:0xf bank_mask:0xf bound_ctrl:1
	v_pk_fma_f32 v[82:83], v[2:3], v[14:15], v[82:83] op_sel_hi:[1,0,1]
	ds_read_b128 v[136:139], v100 offset:29696
	v_add_f32_dpp v78, v78, v78 row_mirror row_mask:0xf bank_mask:0xf bound_ctrl:1
	v_add_f32_dpp v79, v79, v79 row_mirror row_mask:0xf bank_mask:0xf bound_ctrl:1
	v_pk_fma_f32 v[84:85], v[4:5], v[14:15], v[84:85] op_sel:[0,1,0] op_sel_hi:[1,1,1]
	ds_read_b128 v[144:147], v100 offset:30208
	v_pk_fma_f32 v[86:87], v[6:7], v[16:17], v[86:87] op_sel_hi:[1,0,1]
	ds_read_b128 v[148:151], v100 offset:30464
	v_pk_fma_f32 v[88:89], v[8:9], v[16:17], v[88:89] op_sel:[0,1,0] op_sel_hi:[1,1,1]
	v_cndmask_b32_e64 v109, v95, v97, s[50:51]
	v_cndmask_b32_e64 v111, v97, v95, s[50:51]
	v_add_f32_dpp v112, v106, v104 quad_perm:[1,0,3,2] row_mask:0xf bank_mask:0xf bound_ctrl:1
	v_pk_fma_f32 v[2:3], v[78:79], v[22:23], v[82:83] op_sel_hi:[1,0,1]
	v_pk_fma_f32 v[4:5], v[78:79], v[22:23], v[84:85] op_sel:[0,1,0] op_sel_hi:[1,1,1]
	v_pk_fma_f32 v[6:7], v[78:79], v[24:25], v[86:87] op_sel_hi:[1,0,1]
	v_pk_fma_f32 v[8:9], v[78:79], v[24:25], v[88:89] op_sel:[0,1,0] op_sel_hi:[1,1,1]
	v_add_f32_dpp v114, v110, v108 quad_perm:[1,0,3,2] row_mask:0xf bank_mask:0xf bound_ctrl:1
	v_add_f32_dpp v113, v107, v105 quad_perm:[1,0,3,2] row_mask:0xf bank_mask:0xf bound_ctrl:1
	v_add_f32_dpp v115, v111, v109 quad_perm:[1,0,3,2] row_mask:0xf bank_mask:0xf bound_ctrl:1
	s_waitcnt lgkmcnt(5)
; #define LAS __attribute__((address_space(3)))
; __device__ __forceinline__ void phase_scan(CParams& P, LAS unsigned char* lds) {
;     ...
;             f32x4 Ar0, Ar1, Aw0, Aw1, Ak0, Ak1, Aq0, Aq1, Ab0, Ab1, Br0, Br1, Bw0, Bw1, Bk0, Bk1, Bq0, Bq1, Bb0, Bb1; float Avv, Bvv;
; #pragma unroll 1
;             for (int c = 0; c < NCH; ++c) {
;                 __syncthreads();
;                 const LAS float* base = lf + (c & 1) * BUFF + 8 * oct;
;                 SC_LOAD(A, base);
; #pragma unroll 2
;                 for (int j = 0; j < CH; j += 2) { const LAS float* sp = base + j * STEPF;
;                     SC_LOAD(B, sp + STEPF); SC_STEP(A);
;                     SC_LOAD(A, sp + 2 * STEPF);
;                     SC_STEP(B); }
	v_pk_mul_f32 v[78:79], v[2:3], v[30:31] op_sel_hi:[1,0]
	v_pk_mul_f32 v[92:93], v[2:3], v[26:27] op_sel_hi:[1,0]
	v_pk_fma_f32 v[78:79], v[4:5], v[30:31], v[78:79] op_sel:[0,1,0] op_sel_hi:[1,1,1]
	v_pk_fma_f32 v[92:93], v[4:5], v[26:27], v[92:93] op_sel:[0,1,0] op_sel_hi:[1,1,1]
	v_pk_fma_f32 v[78:79], v[6:7], v[32:33], v[78:79] op_sel_hi:[1,0,1]
	v_pk_fma_f32 v[92:93], v[6:7], v[28:29], v[92:93] op_sel_hi:[1,0,1]
	v_pk_fma_f32 v[78:79], v[8:9], v[32:33], v[78:79] op_sel:[0,1,0] op_sel_hi:[1,1,1]
	v_pk_mul_f32 v[82:83], v[74:75], v[38:39] op_sel_hi:[1,0]
	v_pk_fma_f32 v[92:93], v[8:9], v[28:29], v[92:93] op_sel:[0,1,0] op_sel_hi:[1,1,1]
	v_pk_mul_f32 v[84:85], v[74:75], v[38:39] op_sel:[0,1] op_sel_hi:[1,1]
	v_add_f32_dpp v78, v78, v78 quad_perm:[1,0,3,2] row_mask:0xf bank_mask:0xf bound_ctrl:1
	v_add_f32_dpp v79, v79, v79 quad_perm:[1,0,3,2] row_mask:0xf bank_mask:0xf bound_ctrl:1
	v_pk_mul_f32 v[86:87], v[74:75], v[40:41] op_sel_hi:[1,0]
	ds_read_b128 v[10:13], v100 offset:30720
	v_add_f32_dpp v78, v78, v78 quad_perm:[2,3,0,1] row_mask:0xf bank_mask:0xf bound_ctrl:1
	v_add_f32_dpp v79, v79, v79 quad_perm:[2,3,0,1] row_mask:0xf bank_mask:0xf bound_ctrl:1
	v_pk_mul_f32 v[88:89], v[74:75], v[40:41] op_sel:[0,1] op_sel_hi:[1,1]
	ds_read_b128 v[18:21], v100 offset:31232
	v_add_f32_dpp v78, v78, v78 row_half_mirror row_mask:0xf bank_mask:0xf bound_ctrl:1
	v_add_f32_dpp v79, v79, v79 row_half_mirror row_mask:0xf bank_mask:0xf bound_ctrl:1
	v_pk_fma_f32 v[82:83], v[2:3], v[34:35], v[82:83] op_sel_hi:[1,0,1]
	ds_read_b128 v[14:17], v100 offset:30976
	v_add_f32_dpp v78, v78, v78 row_mirror row_mask:0xf bank_mask:0xf bound_ctrl:1
	v_add_f32_dpp v79, v79, v79 row_mirror row_mask:0xf bank_mask:0xf bound_ctrl:1
	v_pk_fma_f32 v[84:85], v[4:5], v[34:35], v[84:85] op_sel:[0,1,0] op_sel_hi:[1,1,1]
	ds_read_b128 v[22:25], v100 offset:31488
	v_pk_fma_f32 v[86:87], v[6:7], v[36:37], v[86:87] op_sel_hi:[1,0,1]
	ds_read_b128 v[26:29], v100 offset:31744
	v_pk_fma_f32 v[88:89], v[8:9], v[36:37], v[88:89] op_sel:[0,1,0] op_sel_hi:[1,1,1]
	ds_read_b128 v[70:73], v101 offset:192
	v_cndmask_b32_e64 v116, v112, v114, s[52:53]
	v_cndmask_b32_e64 v118, v114, v112, s[52:53]
	v_cndmask_b32_e64 v117, v113, v115, s[52:53]
	v_pk_fma_f32 v[2:3], v[78:79], v[42:43], v[82:83] op_sel_hi:[1,0,1]
	v_pk_fma_f32 v[4:5], v[78:79], v[42:43], v[84:85] op_sel:[0,1,0] op_sel_hi:[1,1,1]
	v_pk_fma_f32 v[6:7], v[78:79], v[44:45], v[86:87] op_sel_hi:[1,0,1]
	v_pk_fma_f32 v[8:9], v[78:79], v[44:45], v[88:89] op_sel:[0,1,0] op_sel_hi:[1,1,1]
	v_cndmask_b32_e64 v119, v115, v113, s[52:53]
	v_add_f32_dpp v120, v118, v116 quad_perm:[2,3,0,1] row_mask:0xf bank_mask:0xf bound_ctrl:1
	s_nop 0
	v_add_f32_dpp v121, v119, v117 quad_perm:[2,3,0,1] row_mask:0xf bank_mask:0xf bound_ctrl:1
	s_waitcnt lgkmcnt(6)
	v_pk_mul_f32 v[78:79], v[2:3], v[132:133] op_sel_hi:[1,0]
	v_pk_mul_f32 v[94:95], v[2:3], v[46:47] op_sel_hi:[1,0]
	v_pk_fma_f32 v[78:79], v[4:5], v[132:133], v[78:79] op_sel:[0,1,0] op_sel_hi:[1,1,1]
	v_pk_fma_f32 v[94:95], v[4:5], v[46:47], v[94:95] op_sel:[0,1,0] op_sel_hi:[1,1,1]
	v_pk_fma_f32 v[78:79], v[6:7], v[134:135], v[78:79] op_sel_hi:[1,0,1]
	v_pk_fma_f32 v[94:95], v[6:7], v[48:49], v[94:95] op_sel_hi:[1,0,1]
	v_pk_fma_f32 v[78:79], v[8:9], v[134:135], v[78:79] op_sel:[0,1,0] op_sel_hi:[1,1,1]
	v_pk_mul_f32 v[82:83], v[76:77], v[140:141] op_sel_hi:[1,0]
	v_pk_fma_f32 v[94:95], v[8:9], v[48:49], v[94:95] op_sel:[0,1,0] op_sel_hi:[1,1,1]
	v_pk_mul_f32 v[84:85], v[76:77], v[140:141] op_sel:[0,1] op_sel_hi:[1,1]
	v_add_f32_dpp v78, v78, v78 quad_perm:[1,0,3,2] row_mask:0xf bank_mask:0xf bound_ctrl:1
	v_add_f32_dpp v79, v79, v79 quad_perm:[1,0,3,2] row_mask:0xf bank_mask:0xf bound_ctrl:1
	v_pk_mul_f32 v[86:87], v[76:77], v[142:143] op_sel_hi:[1,0]
	ds_read_b128 v[30:33], v100 offset:32000
	v_add_f32_dpp v78, v78, v78 quad_perm:[2,3,0,1] row_mask:0xf bank_mask:0xf bound_ctrl:1
	v_add_f32_dpp v79, v79, v79 quad_perm:[2,3,0,1] row_mask:0xf bank_mask:0xf bound_ctrl:1
	v_pk_mul_f32 v[88:89], v[76:77], v[142:143] op_sel:[0,1] op_sel_hi:[1,1]
	ds_read_b128 v[38:41], v100 offset:32512
	v_add_f32_dpp v78, v78, v78 row_half_mirror row_mask:0xf bank_mask:0xf bound_ctrl:1
	v_add_f32_dpp v79, v79, v79 row_half_mirror row_mask:0xf bank_mask:0xf bound_ctrl:1
	v_pk_fma_f32 v[82:83], v[2:3], v[136:137], v[82:83] op_sel_hi:[1,0,1]
	ds_read_b128 v[34:37], v100 offset:32256
	v_add_f32_dpp v78, v78, v78 row_mirror row_mask:0xf bank_mask:0xf bound_ctrl:1
	v_add_f32_dpp v79, v79, v79 row_mirror row_mask:0xf bank_mask:0xf bound_ctrl:1
	v_pk_fma_f32 v[84:85], v[4:5], v[136:137], v[84:85] op_sel:[0,1,0] op_sel_hi:[1,1,1]
	ds_read_b128 v[42:45], v100 offset:32768
	v_pk_fma_f32 v[86:87], v[6:7], v[138:139], v[86:87] op_sel_hi:[1,0,1]
	ds_read_b128 v[46:49], v100 offset:33024
	v_pk_fma_f32 v[88:89], v[8:9], v[138:139], v[88:89] op_sel:[0,1,0] op_sel_hi:[1,1,1]
	v_add_f32_dpp v120, v120, v120 row_ror:4 row_mask:0xf bank_mask:0xf bound_ctrl:1
	v_add_f32_dpp v121, v121, v121 row_ror:4 row_mask:0xf bank_mask:0xf bound_ctrl:1
	s_nop 0
	v_add_f32_dpp v120, v120, v120 row_ror:8 row_mask:0xf bank_mask:0xf bound_ctrl:1
	v_pk_fma_f32 v[2:3], v[78:79], v[144:145], v[82:83] op_sel_hi:[1,0,1]
	v_pk_fma_f32 v[4:5], v[78:79], v[144:145], v[84:85] op_sel:[0,1,0] op_sel_hi:[1,1,1]
	v_pk_fma_f32 v[6:7], v[78:79], v[146:147], v[86:87] op_sel_hi:[1,0,1]
	v_pk_fma_f32 v[8:9], v[78:79], v[146:147], v[88:89] op_sel:[0,1,0] op_sel_hi:[1,1,1]
	v_add_f32_dpp v121, v121, v121 row_ror:8 row_mask:0xf bank_mask:0xf bound_ctrl:1
	global_store_dwordx2 v102, v[120:121], s[10:11]
	v_add_u32_e32 v102, s13, v102
	s_waitcnt lgkmcnt(5)
; #define LAS __attribute__((address_space(3)))
; __device__ __forceinline__ void phase_scan(CParams& P, LAS unsigned char* lds) {
;     ...
;             f32x4 Ar0, Ar1, Aw0, Aw1, Ak0, Ak1, Aq0, Aq1, Ab0, Ab1, Br0, Br1, Bw0, Bw1, Bk0, Bk1, Bq0, Bq1, Bb0, Bb1; float Avv, Bvv;
; #pragma unroll 1
;             for (int c = 0; c < NCH; ++c) {
;                 __syncthreads();
;                 const LAS float* base = lf + (c & 1) * BUFF + 8 * oct;
;                 SC_LOAD(A, base);
; #pragma unroll 2
;                 for (int j = 0; j < CH; j += 2) { const LAS float* sp = base + j * STEPF;
;                     SC_LOAD(B, sp + STEPF); SC_STEP(A);
;                     SC_LOAD(A, sp + 2 * STEPF);
;                     SC_STEP(B); }
	v_pk_mul_f32 v[78:79], v[2:3], v[10:11] op_sel_hi:[1,0]
	v_pk_mul_f32 v[96:97], v[2:3], v[148:149] op_sel_hi:[1,0]
	v_pk_fma_f32 v[78:79], v[4:5], v[10:11], v[78:79] op_sel:[0,1,0] op_sel_hi:[1,1,1]
	v_pk_fma_f32 v[96:97], v[4:5], v[148:149], v[96:97] op_sel:[0,1,0] op_sel_hi:[1,1,1]
	v_pk_fma_f32 v[78:79], v[6:7], v[12:13], v[78:79] op_sel_hi:[1,0,1]
	v_pk_fma_f32 v[96:97], v[6:7], v[150:151], v[96:97] op_sel_hi:[1,0,1]
	v_pk_fma_f32 v[78:79], v[8:9], v[12:13], v[78:79] op_sel:[0,1,0] op_sel_hi:[1,1,1]
	v_pk_mul_f32 v[82:83], v[70:71], v[18:19] op_sel_hi:[1,0]
	v_pk_fma_f32 v[96:97], v[8:9], v[150:151], v[96:97] op_sel:[0,1,0] op_sel_hi:[1,1,1]
	v_pk_mul_f32 v[84:85], v[70:71], v[18:19] op_sel:[0,1] op_sel_hi:[1,1]
	v_add_f32_dpp v78, v78, v78 quad_perm:[1,0,3,2] row_mask:0xf bank_mask:0xf bound_ctrl:1
	v_add_f32_dpp v79, v79, v79 quad_perm:[1,0,3,2] row_mask:0xf bank_mask:0xf bound_ctrl:1
	v_pk_mul_f32 v[86:87], v[70:71], v[20:21] op_sel_hi:[1,0]
	ds_read_b128 v[132:135], v100 offset:33280
	v_add_f32_dpp v78, v78, v78 quad_perm:[2,3,0,1] row_mask:0xf bank_mask:0xf bound_ctrl:1
	v_add_f32_dpp v79, v79, v79 quad_perm:[2,3,0,1] row_mask:0xf bank_mask:0xf bound_ctrl:1
	v_pk_mul_f32 v[88:89], v[70:71], v[20:21] op_sel:[0,1] op_sel_hi:[1,1]
	ds_read_b128 v[140:143], v100 offset:33792
	v_add_f32_dpp v78, v78, v78 row_half_mirror row_mask:0xf bank_mask:0xf bound_ctrl:1
	v_add_f32_dpp v79, v79, v79 row_half_mirror row_mask:0xf bank_mask:0xf bound_ctrl:1
	v_pk_fma_f32 v[82:83], v[2:3], v[14:15], v[82:83] op_sel_hi:[1,0,1]
	ds_read_b128 v[136:139], v100 offset:33536
	v_add_f32_dpp v78, v78, v78 row_mirror row_mask:0xf bank_mask:0xf bound_ctrl:1
	v_add_f32_dpp v79, v79, v79 row_mirror row_mask:0xf bank_mask:0xf bound_ctrl:1
	v_pk_fma_f32 v[84:85], v[4:5], v[14:15], v[84:85] op_sel:[0,1,0] op_sel_hi:[1,1,1]
	ds_read_b128 v[144:147], v100 offset:34048
	v_pk_fma_f32 v[86:87], v[6:7], v[16:17], v[86:87] op_sel_hi:[1,0,1]
	ds_read_b128 v[148:151], v100 offset:34304
	v_pk_fma_f32 v[88:89], v[8:9], v[16:17], v[88:89] op_sel:[0,1,0] op_sel_hi:[1,1,1]
	ds_read_b128 v[74:77], v101 offset:208
	v_cndmask_b32_e64 v104, v90, v92, s[50:51]
	v_cndmask_b32_e64 v106, v92, v90, s[50:51]
	v_cndmask_b32_e64 v108, v94, v96, s[50:51]
	v_pk_fma_f32 v[2:3], v[78:79], v[22:23], v[82:83] op_sel_hi:[1,0,1]
	v_pk_fma_f32 v[4:5], v[78:79], v[22:23], v[84:85] op_sel:[0,1,0] op_sel_hi:[1,1,1]
	v_pk_fma_f32 v[6:7], v[78:79], v[24:25], v[86:87] op_sel_hi:[1,0,1]
	v_pk_fma_f32 v[8:9], v[78:79], v[24:25], v[88:89] op_sel:[0,1,0] op_sel_hi:[1,1,1]
	v_cndmask_b32_e64 v110, v96, v94, s[50:51]
	v_cndmask_b32_e64 v105, v91, v93, s[50:51]
	v_cndmask_b32_e64 v107, v93, v91, s[50:51]
	s_waitcnt lgkmcnt(6)
	v_pk_mul_f32 v[78:79], v[2:3], v[30:31] op_sel_hi:[1,0]
	v_pk_mul_f32 v[90:91], v[2:3], v[26:27] op_sel_hi:[1,0]
	v_pk_fma_f32 v[78:79], v[4:5], v[30:31], v[78:79] op_sel:[0,1,0] op_sel_hi:[1,1,1]
	v_pk_fma_f32 v[90:91], v[4:5], v[26:27], v[90:91] op_sel:[0,1,0] op_sel_hi:[1,1,1]
	v_pk_fma_f32 v[78:79], v[6:7], v[32:33], v[78:79] op_sel_hi:[1,0,1]
	v_pk_fma_f32 v[90:91], v[6:7], v[28:29], v[90:91] op_sel_hi:[1,0,1]
	v_pk_fma_f32 v[78:79], v[8:9], v[32:33], v[78:79] op_sel:[0,1,0] op_sel_hi:[1,1,1]
	v_pk_mul_f32 v[82:83], v[72:73], v[38:39] op_sel_hi:[1,0]
	v_pk_fma_f32 v[90:91], v[8:9], v[28:29], v[90:91] op_sel:[0,1,0] op_sel_hi:[1,1,1]
	v_pk_mul_f32 v[84:85], v[72:73], v[38:39] op_sel:[0,1] op_sel_hi:[1,1]
	v_add_f32_dpp v78, v78, v78 quad_perm:[1,0,3,2] row_mask:0xf bank_mask:0xf bound_ctrl:1
	v_add_f32_dpp v79, v79, v79 quad_perm:[1,0,3,2] row_mask:0xf bank_mask:0xf bound_ctrl:1
	v_pk_mul_f32 v[86:87], v[72:73], v[40:41] op_sel_hi:[1,0]
	ds_read_b128 v[10:13], v100 offset:34560
	v_add_f32_dpp v78, v78, v78 quad_perm:[2,3,0,1] row_mask:0xf bank_mask:0xf bound_ctrl:1
	v_add_f32_dpp v79, v79, v79 quad_perm:[2,3,0,1] row_mask:0xf bank_mask:0xf bound_ctrl:1
	v_pk_mul_f32 v[88:89], v[72:73], v[40:41] op_sel:[0,1] op_sel_hi:[1,1]
	ds_read_b128 v[18:21], v100 offset:35072
	v_add_f32_dpp v78, v78, v78 row_half_mirror row_mask:0xf bank_mask:0xf bound_ctrl:1
	v_add_f32_dpp v79, v79, v79 row_half_mirror row_mask:0xf bank_mask:0xf bound_ctrl:1
	v_pk_fma_f32 v[82:83], v[2:3], v[34:35], v[82:83] op_sel_hi:[1,0,1]
	ds_read_b128 v[14:17], v100 offset:34816
	v_add_f32_dpp v78, v78, v78 row_mirror row_mask:0xf bank_mask:0xf bound_ctrl:1
	v_add_f32_dpp v79, v79, v79 row_mirror row_mask:0xf bank_mask:0xf bound_ctrl:1
	v_pk_fma_f32 v[84:85], v[4:5], v[34:35], v[84:85] op_sel:[0,1,0] op_sel_hi:[1,1,1]
	ds_read_b128 v[22:25], v100 offset:35328
	v_pk_fma_f32 v[86:87], v[6:7], v[36:37], v[86:87] op_sel_hi:[1,0,1]
	ds_read_b128 v[26:29], v100 offset:35584
	v_pk_fma_f32 v[88:89], v[8:9], v[36:37], v[88:89] op_sel:[0,1,0] op_sel_hi:[1,1,1]
	v_cndmask_b32_e64 v109, v95, v97, s[50:51]
	v_cndmask_b32_e64 v111, v97, v95, s[50:51]
	v_add_f32_dpp v112, v106, v104 quad_perm:[1,0,3,2] row_mask:0xf bank_mask:0xf bound_ctrl:1
	v_pk_fma_f32 v[2:3], v[78:79], v[42:43], v[82:83] op_sel_hi:[1,0,1]
	v_pk_fma_f32 v[4:5], v[78:79], v[42:43], v[84:85] op_sel:[0,1,0] op_sel_hi:[1,1,1]
	v_pk_fma_f32 v[6:7], v[78:79], v[44:45], v[86:87] op_sel_hi:[1,0,1]
	v_pk_fma_f32 v[8:9], v[78:79], v[44:45], v[88:89] op_sel:[0,1,0] op_sel_hi:[1,1,1]
	v_add_f32_dpp v114, v110, v108 quad_perm:[1,0,3,2] row_mask:0xf bank_mask:0xf bound_ctrl:1
	v_add_f32_dpp v113, v107, v105 quad_perm:[1,0,3,2] row_mask:0xf bank_mask:0xf bound_ctrl:1
	v_add_f32_dpp v115, v111, v109 quad_perm:[1,0,3,2] row_mask:0xf bank_mask:0xf bound_ctrl:1
	s_waitcnt lgkmcnt(5)
; #define LAS __attribute__((address_space(3)))
; __device__ __forceinline__ void phase_scan(CParams& P, LAS unsigned char* lds) {
;     ...
;             f32x4 Ar0, Ar1, Aw0, Aw1, Ak0, Ak1, Aq0, Aq1, Ab0, Ab1, Br0, Br1, Bw0, Bw1, Bk0, Bk1, Bq0, Bq1, Bb0, Bb1; float Avv, Bvv;
; #pragma unroll 1
;             for (int c = 0; c < NCH; ++c) {
;                 __syncthreads();
;                 const LAS float* base = lf + (c & 1) * BUFF + 8 * oct;
;                 SC_LOAD(A, base);
; #pragma unroll 2
;                 for (int j = 0; j < CH; j += 2) { const LAS float* sp = base + j * STEPF;
;                     SC_LOAD(B, sp + STEPF); SC_STEP(A);
;                     SC_LOAD(A, sp + 2 * STEPF);
;                     SC_STEP(B); }
	v_pk_mul_f32 v[78:79], v[2:3], v[132:133] op_sel_hi:[1,0]
	v_pk_mul_f32 v[92:93], v[2:3], v[46:47] op_sel_hi:[1,0]
	v_pk_fma_f32 v[78:79], v[4:5], v[132:133], v[78:79] op_sel:[0,1,0] op_sel_hi:[1,1,1]
	v_pk_fma_f32 v[92:93], v[4:5], v[46:47], v[92:93] op_sel:[0,1,0] op_sel_hi:[1,1,1]
	v_pk_fma_f32 v[78:79], v[6:7], v[134:135], v[78:79] op_sel_hi:[1,0,1]
	v_pk_fma_f32 v[92:93], v[6:7], v[48:49], v[92:93] op_sel_hi:[1,0,1]
	v_pk_fma_f32 v[78:79], v[8:9], v[134:135], v[78:79] op_sel:[0,1,0] op_sel_hi:[1,1,1]
	v_pk_mul_f32 v[82:83], v[74:75], v[140:141] op_sel_hi:[1,0]
	v_pk_fma_f32 v[92:93], v[8:9], v[48:49], v[92:93] op_sel:[0,1,0] op_sel_hi:[1,1,1]
	v_pk_mul_f32 v[84:85], v[74:75], v[140:141] op_sel:[0,1] op_sel_hi:[1,1]
	v_add_f32_dpp v78, v78, v78 quad_perm:[1,0,3,2] row_mask:0xf bank_mask:0xf bound_ctrl:1
	v_add_f32_dpp v79, v79, v79 quad_perm:[1,0,3,2] row_mask:0xf bank_mask:0xf bound_ctrl:1
	v_pk_mul_f32 v[86:87], v[74:75], v[142:143] op_sel_hi:[1,0]
	ds_read_b128 v[30:33], v100 offset:35840
	v_add_f32_dpp v78, v78, v78 quad_perm:[2,3,0,1] row_mask:0xf bank_mask:0xf bound_ctrl:1
	v_add_f32_dpp v79, v79, v79 quad_perm:[2,3,0,1] row_mask:0xf bank_mask:0xf bound_ctrl:1
	v_pk_mul_f32 v[88:89], v[74:75], v[142:143] op_sel:[0,1] op_sel_hi:[1,1]
	ds_read_b128 v[38:41], v100 offset:36352
	v_add_f32_dpp v78, v78, v78 row_half_mirror row_mask:0xf bank_mask:0xf bound_ctrl:1
	v_add_f32_dpp v79, v79, v79 row_half_mirror row_mask:0xf bank_mask:0xf bound_ctrl:1
	v_pk_fma_f32 v[82:83], v[2:3], v[136:137], v[82:83] op_sel_hi:[1,0,1]
	ds_read_b128 v[34:37], v100 offset:36096
	v_add_f32_dpp v78, v78, v78 row_mirror row_mask:0xf bank_mask:0xf bound_ctrl:1
	v_add_f32_dpp v79, v79, v79 row_mirror row_mask:0xf bank_mask:0xf bound_ctrl:1
	v_pk_fma_f32 v[84:85], v[4:5], v[136:137], v[84:85] op_sel:[0,1,0] op_sel_hi:[1,1,1]
	ds_read_b128 v[42:45], v100 offset:36608
	v_pk_fma_f32 v[86:87], v[6:7], v[138:139], v[86:87] op_sel_hi:[1,0,1]
	ds_read_b128 v[46:49], v100 offset:36864
	v_pk_fma_f32 v[88:89], v[8:9], v[138:139], v[88:89] op_sel:[0,1,0] op_sel_hi:[1,1,1]
	ds_read_b128 v[70:73], v101 offset:224
	v_cndmask_b32_e64 v116, v112, v114, s[52:53]
	v_cndmask_b32_e64 v118, v114, v112, s[52:53]
	v_cndmask_b32_e64 v117, v113, v115, s[52:53]
	v_pk_fma_f32 v[2:3], v[78:79], v[144:145], v[82:83] op_sel_hi:[1,0,1]
	v_pk_fma_f32 v[4:5], v[78:79], v[144:145], v[84:85] op_sel:[0,1,0] op_sel_hi:[1,1,1]
	v_pk_fma_f32 v[6:7], v[78:79], v[146:147], v[86:87] op_sel_hi:[1,0,1]
	v_pk_fma_f32 v[8:9], v[78:79], v[146:147], v[88:89] op_sel:[0,1,0] op_sel_hi:[1,1,1]
	v_cndmask_b32_e64 v119, v115, v113, s[52:53]
	v_add_f32_dpp v120, v118, v116 quad_perm:[2,3,0,1] row_mask:0xf bank_mask:0xf bound_ctrl:1
	s_nop 0
	v_add_f32_dpp v121, v119, v117 quad_perm:[2,3,0,1] row_mask:0xf bank_mask:0xf bound_ctrl:1
	s_waitcnt lgkmcnt(6)
	v_pk_mul_f32 v[78:79], v[2:3], v[10:11] op_sel_hi:[1,0]
	v_pk_mul_f32 v[94:95], v[2:3], v[148:149] op_sel_hi:[1,0]
	v_pk_fma_f32 v[78:79], v[4:5], v[10:11], v[78:79] op_sel:[0,1,0] op_sel_hi:[1,1,1]
	v_pk_fma_f32 v[94:95], v[4:5], v[148:149], v[94:95] op_sel:[0,1,0] op_sel_hi:[1,1,1]
	v_pk_fma_f32 v[78:79], v[6:7], v[12:13], v[78:79] op_sel_hi:[1,0,1]
	v_pk_fma_f32 v[94:95], v[6:7], v[150:151], v[94:95] op_sel_hi:[1,0,1]
	v_pk_fma_f32 v[78:79], v[8:9], v[12:13], v[78:79] op_sel:[0,1,0] op_sel_hi:[1,1,1]
	v_pk_mul_f32 v[82:83], v[76:77], v[18:19] op_sel_hi:[1,0]
	v_pk_fma_f32 v[94:95], v[8:9], v[150:151], v[94:95] op_sel:[0,1,0] op_sel_hi:[1,1,1]
	v_pk_mul_f32 v[84:85], v[76:77], v[18:19] op_sel:[0,1] op_sel_hi:[1,1]
	v_add_f32_dpp v78, v78, v78 quad_perm:[1,0,3,2] row_mask:0xf bank_mask:0xf bound_ctrl:1
	v_add_f32_dpp v79, v79, v79 quad_perm:[1,0,3,2] row_mask:0xf bank_mask:0xf bound_ctrl:1
	v_pk_mul_f32 v[86:87], v[76:77], v[20:21] op_sel_hi:[1,0]
	ds_read_b128 v[132:135], v100 offset:37120
	v_add_f32_dpp v78, v78, v78 quad_perm:[2,3,0,1] row_mask:0xf bank_mask:0xf bound_ctrl:1
	v_add_f32_dpp v79, v79, v79 quad_perm:[2,3,0,1] row_mask:0xf bank_mask:0xf bound_ctrl:1
	v_pk_mul_f32 v[88:89], v[76:77], v[20:21] op_sel:[0,1] op_sel_hi:[1,1]
	ds_read_b128 v[140:143], v100 offset:37632
	v_add_f32_dpp v78, v78, v78 row_half_mirror row_mask:0xf bank_mask:0xf bound_ctrl:1
	v_add_f32_dpp v79, v79, v79 row_half_mirror row_mask:0xf bank_mask:0xf bound_ctrl:1
	v_pk_fma_f32 v[82:83], v[2:3], v[14:15], v[82:83] op_sel_hi:[1,0,1]
	ds_read_b128 v[136:139], v100 offset:37376
	v_add_f32_dpp v78, v78, v78 row_mirror row_mask:0xf bank_mask:0xf bound_ctrl:1
	v_add_f32_dpp v79, v79, v79 row_mirror row_mask:0xf bank_mask:0xf bound_ctrl:1
	v_pk_fma_f32 v[84:85], v[4:5], v[14:15], v[84:85] op_sel:[0,1,0] op_sel_hi:[1,1,1]
	ds_read_b128 v[144:147], v100 offset:37888
	v_pk_fma_f32 v[86:87], v[6:7], v[16:17], v[86:87] op_sel_hi:[1,0,1]
	ds_read_b128 v[148:151], v100 offset:38144
	v_pk_fma_f32 v[88:89], v[8:9], v[16:17], v[88:89] op_sel:[0,1,0] op_sel_hi:[1,1,1]
	v_add_f32_dpp v120, v120, v120 row_ror:4 row_mask:0xf bank_mask:0xf bound_ctrl:1
	v_add_f32_dpp v121, v121, v121 row_ror:4 row_mask:0xf bank_mask:0xf bound_ctrl:1
	s_nop 0
	v_add_f32_dpp v120, v120, v120 row_ror:8 row_mask:0xf bank_mask:0xf bound_ctrl:1
	v_pk_fma_f32 v[2:3], v[78:79], v[22:23], v[82:83] op_sel_hi:[1,0,1]
	v_pk_fma_f32 v[4:5], v[78:79], v[22:23], v[84:85] op_sel:[0,1,0] op_sel_hi:[1,1,1]
	v_pk_fma_f32 v[6:7], v[78:79], v[24:25], v[86:87] op_sel_hi:[1,0,1]
	v_pk_fma_f32 v[8:9], v[78:79], v[24:25], v[88:89] op_sel:[0,1,0] op_sel_hi:[1,1,1]
	v_add_f32_dpp v121, v121, v121 row_ror:8 row_mask:0xf bank_mask:0xf bound_ctrl:1
	global_store_dwordx2 v102, v[120:121], s[10:11]
	v_add_u32_e32 v102, s13, v102
	s_waitcnt lgkmcnt(5)
; #define LAS __attribute__((address_space(3)))
; __device__ __forceinline__ void phase_scan(CParams& P, LAS unsigned char* lds) {
;     ...
;             f32x4 Ar0, Ar1, Aw0, Aw1, Ak0, Ak1, Aq0, Aq1, Ab0, Ab1, Br0, Br1, Bw0, Bw1, Bk0, Bk1, Bq0, Bq1, Bb0, Bb1; float Avv, Bvv;
; #pragma unroll 1
;             for (int c = 0; c < NCH; ++c) {
;                 __syncthreads();
;                 const LAS float* base = lf + (c & 1) * BUFF + 8 * oct;
;                 SC_LOAD(A, base);
; #pragma unroll 2
;                 for (int j = 0; j < CH; j += 2) { const LAS float* sp = base + j * STEPF;
;                     SC_LOAD(B, sp + STEPF); SC_STEP(A);
;                     SC_LOAD(A, sp + 2 * STEPF);
;                     SC_STEP(B); }
	v_pk_mul_f32 v[78:79], v[2:3], v[30:31] op_sel_hi:[1,0]
	v_pk_mul_f32 v[96:97], v[2:3], v[26:27] op_sel_hi:[1,0]
	v_pk_fma_f32 v[78:79], v[4:5], v[30:31], v[78:79] op_sel:[0,1,0] op_sel_hi:[1,1,1]
	v_pk_fma_f32 v[96:97], v[4:5], v[26:27], v[96:97] op_sel:[0,1,0] op_sel_hi:[1,1,1]
	v_pk_fma_f32 v[78:79], v[6:7], v[32:33], v[78:79] op_sel_hi:[1,0,1]
	v_pk_fma_f32 v[96:97], v[6:7], v[28:29], v[96:97] op_sel_hi:[1,0,1]
	v_pk_fma_f32 v[78:79], v[8:9], v[32:33], v[78:79] op_sel:[0,1,0] op_sel_hi:[1,1,1]
	v_pk_mul_f32 v[82:83], v[70:71], v[38:39] op_sel_hi:[1,0]
	v_pk_fma_f32 v[96:97], v[8:9], v[28:29], v[96:97] op_sel:[0,1,0] op_sel_hi:[1,1,1]
	v_pk_mul_f32 v[84:85], v[70:71], v[38:39] op_sel:[0,1] op_sel_hi:[1,1]
	v_add_f32_dpp v78, v78, v78 quad_perm:[1,0,3,2] row_mask:0xf bank_mask:0xf bound_ctrl:1
	v_add_f32_dpp v79, v79, v79 quad_perm:[1,0,3,2] row_mask:0xf bank_mask:0xf bound_ctrl:1
	v_pk_mul_f32 v[86:87], v[70:71], v[40:41] op_sel_hi:[1,0]
	ds_read_b128 v[10:13], v100 offset:38400
	v_add_f32_dpp v78, v78, v78 quad_perm:[2,3,0,1] row_mask:0xf bank_mask:0xf bound_ctrl:1
	v_add_f32_dpp v79, v79, v79 quad_perm:[2,3,0,1] row_mask:0xf bank_mask:0xf bound_ctrl:1
	v_pk_mul_f32 v[88:89], v[70:71], v[40:41] op_sel:[0,1] op_sel_hi:[1,1]
	ds_read_b128 v[18:21], v100 offset:38912
	v_add_f32_dpp v78, v78, v78 row_half_mirror row_mask:0xf bank_mask:0xf bound_ctrl:1
	v_add_f32_dpp v79, v79, v79 row_half_mirror row_mask:0xf bank_mask:0xf bound_ctrl:1
	v_pk_fma_f32 v[82:83], v[2:3], v[34:35], v[82:83] op_sel_hi:[1,0,1]
	ds_read_b128 v[14:17], v100 offset:38656
	v_add_f32_dpp v78, v78, v78 row_mirror row_mask:0xf bank_mask:0xf bound_ctrl:1
	v_add_f32_dpp v79, v79, v79 row_mirror row_mask:0xf bank_mask:0xf bound_ctrl:1
	v_pk_fma_f32 v[84:85], v[4:5], v[34:35], v[84:85] op_sel:[0,1,0] op_sel_hi:[1,1,1]
	ds_read_b128 v[22:25], v100 offset:39168
	v_pk_fma_f32 v[86:87], v[6:7], v[36:37], v[86:87] op_sel_hi:[1,0,1]
	ds_read_b128 v[26:29], v100 offset:39424
	v_pk_fma_f32 v[88:89], v[8:9], v[36:37], v[88:89] op_sel:[0,1,0] op_sel_hi:[1,1,1]
	ds_read_b128 v[74:77], v101 offset:240
	v_cndmask_b32_e64 v104, v90, v92, s[50:51]
	v_cndmask_b32_e64 v106, v92, v90, s[50:51]
	v_cndmask_b32_e64 v108, v94, v96, s[50:51]
	v_pk_fma_f32 v[2:3], v[78:79], v[42:43], v[82:83] op_sel_hi:[1,0,1]
	v_pk_fma_f32 v[4:5], v[78:79], v[42:43], v[84:85] op_sel:[0,1,0] op_sel_hi:[1,1,1]
	v_pk_fma_f32 v[6:7], v[78:79], v[44:45], v[86:87] op_sel_hi:[1,0,1]
	v_pk_fma_f32 v[8:9], v[78:79], v[44:45], v[88:89] op_sel:[0,1,0] op_sel_hi:[1,1,1]
	v_cndmask_b32_e64 v110, v96, v94, s[50:51]
	v_cndmask_b32_e64 v105, v91, v93, s[50:51]
	v_cndmask_b32_e64 v107, v93, v91, s[50:51]
	s_waitcnt lgkmcnt(6)
	v_pk_mul_f32 v[78:79], v[2:3], v[132:133] op_sel_hi:[1,0]
	v_pk_mul_f32 v[90:91], v[2:3], v[46:47] op_sel_hi:[1,0]
	v_pk_fma_f32 v[78:79], v[4:5], v[132:133], v[78:79] op_sel:[0,1,0] op_sel_hi:[1,1,1]
	v_pk_fma_f32 v[90:91], v[4:5], v[46:47], v[90:91] op_sel:[0,1,0] op_sel_hi:[1,1,1]
	v_pk_fma_f32 v[78:79], v[6:7], v[134:135], v[78:79] op_sel_hi:[1,0,1]
	v_pk_fma_f32 v[90:91], v[6:7], v[48:49], v[90:91] op_sel_hi:[1,0,1]
	v_pk_fma_f32 v[78:79], v[8:9], v[134:135], v[78:79] op_sel:[0,1,0] op_sel_hi:[1,1,1]
	v_pk_mul_f32 v[82:83], v[72:73], v[140:141] op_sel_hi:[1,0]
	v_pk_fma_f32 v[90:91], v[8:9], v[48:49], v[90:91] op_sel:[0,1,0] op_sel_hi:[1,1,1]
	v_pk_mul_f32 v[84:85], v[72:73], v[140:141] op_sel:[0,1] op_sel_hi:[1,1]
	v_add_f32_dpp v78, v78, v78 quad_perm:[1,0,3,2] row_mask:0xf bank_mask:0xf bound_ctrl:1
	v_add_f32_dpp v79, v79, v79 quad_perm:[1,0,3,2] row_mask:0xf bank_mask:0xf bound_ctrl:1
	v_pk_mul_f32 v[86:87], v[72:73], v[142:143] op_sel_hi:[1,0]
	ds_read_b128 v[30:33], v100 offset:39680
	v_add_f32_dpp v78, v78, v78 quad_perm:[2,3,0,1] row_mask:0xf bank_mask:0xf bound_ctrl:1
	v_add_f32_dpp v79, v79, v79 quad_perm:[2,3,0,1] row_mask:0xf bank_mask:0xf bound_ctrl:1
	v_pk_mul_f32 v[88:89], v[72:73], v[142:143] op_sel:[0,1] op_sel_hi:[1,1]
	ds_read_b128 v[38:41], v100 offset:40192
	v_add_f32_dpp v78, v78, v78 row_half_mirror row_mask:0xf bank_mask:0xf bound_ctrl:1
	v_add_f32_dpp v79, v79, v79 row_half_mirror row_mask:0xf bank_mask:0xf bound_ctrl:1
	v_pk_fma_f32 v[82:83], v[2:3], v[136:137], v[82:83] op_sel_hi:[1,0,1]
	ds_read_b128 v[34:37], v100 offset:39936
	v_add_f32_dpp v78, v78, v78 row_mirror row_mask:0xf bank_mask:0xf bound_ctrl:1
	v_add_f32_dpp v79, v79, v79 row_mirror row_mask:0xf bank_mask:0xf bound_ctrl:1
	v_pk_fma_f32 v[84:85], v[4:5], v[136:137], v[84:85] op_sel:[0,1,0] op_sel_hi:[1,1,1]
	ds_read_b128 v[42:45], v100 offset:40448
	v_pk_fma_f32 v[86:87], v[6:7], v[138:139], v[86:87] op_sel_hi:[1,0,1]
	ds_read_b128 v[46:49], v100 offset:40704
	v_pk_fma_f32 v[88:89], v[8:9], v[138:139], v[88:89] op_sel:[0,1,0] op_sel_hi:[1,1,1]
	v_cndmask_b32_e64 v109, v95, v97, s[50:51]
	v_cndmask_b32_e64 v111, v97, v95, s[50:51]
	v_add_f32_dpp v112, v106, v104 quad_perm:[1,0,3,2] row_mask:0xf bank_mask:0xf bound_ctrl:1
	v_pk_fma_f32 v[2:3], v[78:79], v[144:145], v[82:83] op_sel_hi:[1,0,1]
	v_pk_fma_f32 v[4:5], v[78:79], v[144:145], v[84:85] op_sel:[0,1,0] op_sel_hi:[1,1,1]
	v_pk_fma_f32 v[6:7], v[78:79], v[146:147], v[86:87] op_sel_hi:[1,0,1]
	v_pk_fma_f32 v[8:9], v[78:79], v[146:147], v[88:89] op_sel:[0,1,0] op_sel_hi:[1,1,1]
	v_add_f32_dpp v114, v110, v108 quad_perm:[1,0,3,2] row_mask:0xf bank_mask:0xf bound_ctrl:1
	v_add_f32_dpp v113, v107, v105 quad_perm:[1,0,3,2] row_mask:0xf bank_mask:0xf bound_ctrl:1
	v_add_f32_dpp v115, v111, v109 quad_perm:[1,0,3,2] row_mask:0xf bank_mask:0xf bound_ctrl:1
	s_waitcnt lgkmcnt(5)
; #define LAS __attribute__((address_space(3)))
; __device__ __forceinline__ void phase_scan(CParams& P, LAS unsigned char* lds) {
;     ...
;             f32x4 Ar0, Ar1, Aw0, Aw1, Ak0, Ak1, Aq0, Aq1, Ab0, Ab1, Br0, Br1, Bw0, Bw1, Bk0, Bk1, Bq0, Bq1, Bb0, Bb1; float Avv, Bvv;
; #pragma unroll 1
;             for (int c = 0; c < NCH; ++c) {
;                 __syncthreads();
;                 const LAS float* base = lf + (c & 1) * BUFF + 8 * oct;
;                 SC_LOAD(A, base);
; #pragma unroll 2
;                 for (int j = 0; j < CH; j += 2) { const LAS float* sp = base + j * STEPF;
;                     SC_LOAD(B, sp + STEPF); SC_STEP(A);
;                     SC_LOAD(A, sp + 2 * STEPF);
;                     SC_STEP(B); }
;             }
	v_pk_mul_f32 v[78:79], v[2:3], v[10:11] op_sel_hi:[1,0]
	v_pk_mul_f32 v[92:93], v[2:3], v[148:149] op_sel_hi:[1,0]
	v_pk_fma_f32 v[78:79], v[4:5], v[10:11], v[78:79] op_sel:[0,1,0] op_sel_hi:[1,1,1]
	v_pk_fma_f32 v[92:93], v[4:5], v[148:149], v[92:93] op_sel:[0,1,0] op_sel_hi:[1,1,1]
	v_pk_fma_f32 v[78:79], v[6:7], v[12:13], v[78:79] op_sel_hi:[1,0,1]
	v_pk_fma_f32 v[92:93], v[6:7], v[150:151], v[92:93] op_sel_hi:[1,0,1]
	v_pk_fma_f32 v[78:79], v[8:9], v[12:13], v[78:79] op_sel:[0,1,0] op_sel_hi:[1,1,1]
	v_pk_mul_f32 v[82:83], v[74:75], v[18:19] op_sel_hi:[1,0]
	v_pk_fma_f32 v[92:93], v[8:9], v[150:151], v[92:93] op_sel:[0,1,0] op_sel_hi:[1,1,1]
	v_pk_mul_f32 v[84:85], v[74:75], v[18:19] op_sel:[0,1] op_sel_hi:[1,1]
	v_add_f32_dpp v78, v78, v78 quad_perm:[1,0,3,2] row_mask:0xf bank_mask:0xf bound_ctrl:1
	v_add_f32_dpp v79, v79, v79 quad_perm:[1,0,3,2] row_mask:0xf bank_mask:0xf bound_ctrl:1
	v_pk_mul_f32 v[86:87], v[74:75], v[20:21] op_sel_hi:[1,0]
	v_add_f32_dpp v78, v78, v78 quad_perm:[2,3,0,1] row_mask:0xf bank_mask:0xf bound_ctrl:1
	v_add_f32_dpp v79, v79, v79 quad_perm:[2,3,0,1] row_mask:0xf bank_mask:0xf bound_ctrl:1
	v_pk_mul_f32 v[88:89], v[74:75], v[20:21] op_sel:[0,1] op_sel_hi:[1,1]
	v_add_f32_dpp v78, v78, v78 row_half_mirror row_mask:0xf bank_mask:0xf bound_ctrl:1
	v_add_f32_dpp v79, v79, v79 row_half_mirror row_mask:0xf bank_mask:0xf bound_ctrl:1
	v_pk_fma_f32 v[82:83], v[2:3], v[14:15], v[82:83] op_sel_hi:[1,0,1]
	v_add_f32_dpp v78, v78, v78 row_mirror row_mask:0xf bank_mask:0xf bound_ctrl:1
	v_add_f32_dpp v79, v79, v79 row_mirror row_mask:0xf bank_mask:0xf bound_ctrl:1
	v_pk_fma_f32 v[84:85], v[4:5], v[14:15], v[84:85] op_sel:[0,1,0] op_sel_hi:[1,1,1]
	v_pk_fma_f32 v[86:87], v[6:7], v[16:17], v[86:87] op_sel_hi:[1,0,1]
	v_pk_fma_f32 v[88:89], v[8:9], v[16:17], v[88:89] op_sel:[0,1,0] op_sel_hi:[1,1,1]
	v_cndmask_b32_e64 v116, v112, v114, s[52:53]
	v_cndmask_b32_e64 v118, v114, v112, s[52:53]
	v_cndmask_b32_e64 v117, v113, v115, s[52:53]
	v_pk_fma_f32 v[2:3], v[78:79], v[22:23], v[82:83] op_sel_hi:[1,0,1]
	v_pk_fma_f32 v[4:5], v[78:79], v[22:23], v[84:85] op_sel:[0,1,0] op_sel_hi:[1,1,1]
	v_pk_fma_f32 v[6:7], v[78:79], v[24:25], v[86:87] op_sel_hi:[1,0,1]
	v_pk_fma_f32 v[8:9], v[78:79], v[24:25], v[88:89] op_sel:[0,1,0] op_sel_hi:[1,1,1]
	v_cndmask_b32_e64 v119, v115, v113, s[52:53]
	v_add_f32_dpp v120, v118, v116 quad_perm:[2,3,0,1] row_mask:0xf bank_mask:0xf bound_ctrl:1
	s_nop 0
	v_add_f32_dpp v121, v119, v117 quad_perm:[2,3,0,1] row_mask:0xf bank_mask:0xf bound_ctrl:1
	s_waitcnt lgkmcnt(0)
	v_pk_mul_f32 v[78:79], v[2:3], v[30:31] op_sel_hi:[1,0]
	v_pk_mul_f32 v[94:95], v[2:3], v[26:27] op_sel_hi:[1,0]
	v_pk_fma_f32 v[78:79], v[4:5], v[30:31], v[78:79] op_sel:[0,1,0] op_sel_hi:[1,1,1]
	v_pk_fma_f32 v[94:95], v[4:5], v[26:27], v[94:95] op_sel:[0,1,0] op_sel_hi:[1,1,1]
	v_pk_fma_f32 v[78:79], v[6:7], v[32:33], v[78:79] op_sel_hi:[1,0,1]
	v_pk_fma_f32 v[94:95], v[6:7], v[28:29], v[94:95] op_sel_hi:[1,0,1]
	v_pk_fma_f32 v[78:79], v[8:9], v[32:33], v[78:79] op_sel:[0,1,0] op_sel_hi:[1,1,1]
	v_pk_mul_f32 v[82:83], v[76:77], v[38:39] op_sel_hi:[1,0]
	v_pk_fma_f32 v[94:95], v[8:9], v[28:29], v[94:95] op_sel:[0,1,0] op_sel_hi:[1,1,1]
	v_pk_mul_f32 v[84:85], v[76:77], v[38:39] op_sel:[0,1] op_sel_hi:[1,1]
	v_add_f32_dpp v78, v78, v78 quad_perm:[1,0,3,2] row_mask:0xf bank_mask:0xf bound_ctrl:1
	v_add_f32_dpp v79, v79, v79 quad_perm:[1,0,3,2] row_mask:0xf bank_mask:0xf bound_ctrl:1
	v_pk_mul_f32 v[86:87], v[76:77], v[40:41] op_sel_hi:[1,0]
	v_add_f32_dpp v78, v78, v78 quad_perm:[2,3,0,1] row_mask:0xf bank_mask:0xf bound_ctrl:1
	v_add_f32_dpp v79, v79, v79 quad_perm:[2,3,0,1] row_mask:0xf bank_mask:0xf bound_ctrl:1
	v_pk_mul_f32 v[88:89], v[76:77], v[40:41] op_sel:[0,1] op_sel_hi:[1,1]
	v_add_f32_dpp v78, v78, v78 row_half_mirror row_mask:0xf bank_mask:0xf bound_ctrl:1
	v_add_f32_dpp v79, v79, v79 row_half_mirror row_mask:0xf bank_mask:0xf bound_ctrl:1
	v_pk_fma_f32 v[82:83], v[2:3], v[34:35], v[82:83] op_sel_hi:[1,0,1]
	v_add_f32_dpp v78, v78, v78 row_mirror row_mask:0xf bank_mask:0xf bound_ctrl:1
	v_add_f32_dpp v79, v79, v79 row_mirror row_mask:0xf bank_mask:0xf bound_ctrl:1
	v_pk_fma_f32 v[84:85], v[4:5], v[34:35], v[84:85] op_sel:[0,1,0] op_sel_hi:[1,1,1]
	v_pk_fma_f32 v[86:87], v[6:7], v[36:37], v[86:87] op_sel_hi:[1,0,1]
	v_pk_fma_f32 v[88:89], v[8:9], v[36:37], v[88:89] op_sel:[0,1,0] op_sel_hi:[1,1,1]
	v_add_f32_dpp v120, v120, v120 row_ror:4 row_mask:0xf bank_mask:0xf bound_ctrl:1
	v_add_f32_dpp v121, v121, v121 row_ror:4 row_mask:0xf bank_mask:0xf bound_ctrl:1
	s_nop 0
	v_add_f32_dpp v120, v120, v120 row_ror:8 row_mask:0xf bank_mask:0xf bound_ctrl:1
	v_pk_fma_f32 v[2:3], v[78:79], v[42:43], v[82:83] op_sel_hi:[1,0,1]
	v_pk_fma_f32 v[4:5], v[78:79], v[42:43], v[84:85] op_sel:[0,1,0] op_sel_hi:[1,1,1]
	v_pk_fma_f32 v[6:7], v[78:79], v[44:45], v[86:87] op_sel_hi:[1,0,1]
	v_pk_fma_f32 v[8:9], v[78:79], v[44:45], v[88:89] op_sel:[0,1,0] op_sel_hi:[1,1,1]
	v_add_f32_dpp v121, v121, v121 row_ror:8 row_mask:0xf bank_mask:0xf bound_ctrl:1
	global_store_dwordx2 v102, v[120:121], s[10:11]
	v_add_u32_e32 v102, s13, v102
	v_pk_mul_f32 v[96:97], v[2:3], v[46:47] op_sel_hi:[1,0]
	v_pk_fma_f32 v[96:97], v[4:5], v[46:47], v[96:97] op_sel:[0,1,0] op_sel_hi:[1,1,1]
	v_pk_fma_f32 v[96:97], v[6:7], v[48:49], v[96:97] op_sel_hi:[1,0,1]
	v_pk_fma_f32 v[96:97], v[8:9], v[48:49], v[96:97] op_sel:[0,1,0] op_sel_hi:[1,1,1]
	v_cndmask_b32_e64 v104, v90, v92, s[50:51]
	v_cndmask_b32_e64 v106, v92, v90, s[50:51]
	v_cndmask_b32_e64 v108, v94, v96, s[50:51]
	v_cndmask_b32_e64 v110, v96, v94, s[50:51]
	v_cndmask_b32_e64 v105, v91, v93, s[50:51]
	v_cndmask_b32_e64 v107, v93, v91, s[50:51]
	v_cndmask_b32_e64 v109, v95, v97, s[50:51]
	v_cndmask_b32_e64 v111, v97, v95, s[50:51]
	v_add_f32_dpp v112, v106, v104 quad_perm:[1,0,3,2] row_mask:0xf bank_mask:0xf bound_ctrl:1
	v_add_f32_dpp v114, v110, v108 quad_perm:[1,0,3,2] row_mask:0xf bank_mask:0xf bound_ctrl:1
	v_add_f32_dpp v113, v107, v105 quad_perm:[1,0,3,2] row_mask:0xf bank_mask:0xf bound_ctrl:1
	v_add_f32_dpp v115, v111, v109 quad_perm:[1,0,3,2] row_mask:0xf bank_mask:0xf bound_ctrl:1
	v_cndmask_b32_e64 v116, v112, v114, s[52:53]
	v_cndmask_b32_e64 v118, v114, v112, s[52:53]
	v_cndmask_b32_e64 v117, v113, v115, s[52:53]
	v_cndmask_b32_e64 v119, v115, v113, s[52:53]
	v_add_f32_dpp v120, v118, v116 quad_perm:[2,3,0,1] row_mask:0xf bank_mask:0xf bound_ctrl:1
	s_nop 0
	v_add_f32_dpp v121, v119, v117 quad_perm:[2,3,0,1] row_mask:0xf bank_mask:0xf bound_ctrl:1
	v_add_f32_dpp v120, v120, v120 row_ror:4 row_mask:0xf bank_mask:0xf bound_ctrl:1
	s_nop 0
	v_add_f32_dpp v121, v121, v121 row_ror:4 row_mask:0xf bank_mask:0xf bound_ctrl:1
	v_add_f32_dpp v120, v120, v120 row_ror:8 row_mask:0xf bank_mask:0xf bound_ctrl:1
	s_nop 0
	v_add_f32_dpp v121, v121, v121 row_ror:8 row_mask:0xf bank_mask:0xf bound_ctrl:1
	global_store_dwordx2 v102, v[120:121], s[10:11]
	v_add_u32_e32 v102, s13, v102
	s_xor_b32 s14, s14, 0xb000
	s_add_i32 s12, s12, 1
	s_cmp_lt_u32 s12, 0x80
	s_cbranch_scc1 .Lr2_chunk
; __device__ __forceinline__ void phase_scan(CParams& P, LAS unsigned char* lds) {
;     ...
;             __builtin_amdgcn_s_setprio(0);
;             __syncthreads();
;         }
;     }
;     __syncthreads();
.Lr2_done:
.LBB0_605:
	s_mov_b64 s[4:5], 0
	s_waitcnt vmcnt(0)
	s_barrier
